# conversion-loop trims + peeled C=0 first iteration with relaxed post-epilogue waits (G1,G4) + K-loop prologues issue all 7 half-tile DMA groups before the first wait
# baseline (speedup 1.0000x reference)
; #define PG8_STAGE(bufoff, gbase, voff) do { _Pragma("unroll") for (int _i = 0; _i < 2; ++_i) \
;         __builtin_amdgcn_global_load_lds((const unsigned*)((const char*)(gbase) + (voff)[_i]), (PG8_LAS unsigned*)(lds + (bufoff) + ldsw + _i * 8192), 16, 0, 0); } while (0)
; #define PG8_WAIT_V(n) asm volatile("s_waitcnt vmcnt(" #n ")" ::: "memory")
; #define PG8_BAR __builtin_amdgcn_s_barrier()
; template <class Epi, class Sched, bool ALIGN_EPI = false, bool SP2 = false, bool KHOOK = false>
; __device__ __forceinline__ void gemm_phase(PG8_LAS unsigned char* lds, const Gemm g, const Sched& S, const Epi& E, const int tid_in) {
;     ...
;     if constexpr (SP2) {
;         PG8_STAGE(PG8_SB(0, 0), cB, voffB); PG8_STAGE(PG8_SB(0, 1), cB + hstep, voffB); PG8_STAGE(PG8_SA(0, 0), cA, voffA); PG8_STAGE(PG8_SA(0, 1), cA + hstep, voffA);
;         if (wr == 1) PG8_BAR;
;         PG8_WAIT_V(2); PG8_BAR;
;         PG8_STAGE(PG8_SB(1, 0), cB + kstep, voffB); PG8_STAGE(PG8_SA(1, 0), cA + kstep, voffA); PG8_STAGE(PG8_SB(1, 1), cB + hstep + kstep, voffB);
;         PG8_WAIT_V(6); PG8_BAR;
.LBB0_256:
	v_lshrrev_b32_e32 v16, 1, v6
	v_and_b32_e32 v16, 24, v16
	v_and_b32_e32 v7, 15, v6
	v_lshlrev_b32_e32 v17, 1, v16
	v_lshlrev_b32_e32 v6, 2, v6
	v_lshl_or_b32 v140, s14, 6, v7
	v_lshl_or_b32 v7, v7, 6, v17
	s_lshl_b32 s11, s14, 13
	v_and_b32_e32 v6, 32, v6
	s_lshl_b32 s9, s9, 5
	v_bitop3_b32 v17, v7, s11, v6 bitop3:0xde
	s_and_b32 s11, s9, 0x60
	v_lshl_add_u64 v[8:9], s[52:53], 0, v[32:33]
	v_mov_b32_e32 v135, v33
	s_lshl_b32 s9, s11, 7
	v_lshl_add_u64 v[10:11], s[52:53], 0, v[134:135]
	v_mov_b32_e32 v131, v33
	v_bitop3_b32 v141, s9, v7, v6 bitop3:0xf6
	s_add_i32 m0, s13, 0x18000
	v_lshl_add_u64 v[6:7], v[8:9], 0, s[90:91]
	v_lshl_add_u64 v[12:13], s[48:49], 0, v[130:131]
	v_mov_b32_e32 v133, v33
	global_load_lds_dwordx4 v[6:7], off
	v_lshl_add_u64 v[6:7], v[10:11], 0, s[90:91]
	s_add_i32 m0, s13, 0x1a000
	s_add_i32 s39, s13, 0x8000
	s_add_i32 s40, s13, 0xa000
	v_lshl_add_u64 v[14:15], s[48:49], 0, v[132:133]
	global_load_lds_dwordx4 v[6:7], off
	v_lshl_add_u64 v[6:7], v[12:13], 0, s[90:91]
	s_mov_b32 m0, s39
	s_add_u32 s14, s52, 0x80080
	global_load_lds_dwordx4 v[6:7], off
	v_lshl_add_u64 v[6:7], v[14:15], 0, s[90:91]
	s_mov_b32 m0, s40
	s_addc_u32 s15, s53, 0
	global_load_lds_dwordx4 v[6:7], off
	s_add_i32 m0, s13, 0x1c000
	v_lshl_add_u64 v[6:7], s[14:15], 0, v[32:33]
	global_load_lds_dwordx4 v[6:7], off
	v_lshl_add_u64 v[6:7], s[14:15], 0, v[134:135]
	s_add_i32 m0, s13, 0x1e000
	s_cmpk_lt_u32 s8, 0x100
	global_load_lds_dwordx4 v[6:7], off
	s_waitcnt vmcnt(2)
	s_barrier
	v_lshlrev_b32_e32 v6, 15, v0
	v_and_b32_e32 v6, 0xffff0000, v6
	v_lshl_add_u32 v1, v1, 12, v6
	v_and_b32_e32 v0, 1, v0
	v_lshl_or_b32 v0, v0, 6, v1
	v_lshl_add_u32 v136, v2, 1, v0
	v_lshlrev_b32_e32 v0, 15, v3
	v_and_b32_e32 v0, 0xffff0000, v0
	s_waitcnt vmcnt(6)
	v_lshl_add_u32 v0, v4, 12, v0
	v_and_b32_e32 v1, 1, v3
	v_lshl_or_b32 v0, v1, 6, v0
	s_cselect_b64 s[8:9], -1, 0
	v_or_b32_e32 v142, s11, v16
	v_mov_b32_e32 v137, v33
	v_lshl_add_u32 v138, v5, 1, v0
	v_mov_b32_e32 v139, v33
	s_mov_b32 s41, 0
	v_add_u32_e32 v143, 0, v17
	s_barrier
	s_waitcnt vmcnt(0)
	s_branch .LBB0_259

; #define GPROBE_BEGIN(id) do { if (((PROBE_GEMM_SEL >> (id)) & 1) && blockIdx.x == 0 && tid_in < 64 && g.N == 20480) { volatile PG8_LAS unsigned long long* PW_ = (volatile PG8_LAS unsigned long long*)(lds + 163840 - 512 + 64); PW_[0] = __builtin_amdgcn_s_memrealtime(); } } while (0)
; #define GPROBE_END(id) do { if (((PROBE_GEMM_SEL >> (id)) & 1) && blockIdx.x == 0 && tid_in < 64 && g.N == 20480) { volatile PG8_LAS unsigned long long* PW_ = (volatile PG8_LAS unsigned long long*)(lds + 163840 - 512 + 64); PW_[1] += __builtin_amdgcn_s_memrealtime() - PW_[0]; } } while (0)
; #define PG8_STAGE(bufoff, gbase, voff) do { _Pragma("unroll") for (int _i = 0; _i < 2; ++_i) \
;         __builtin_amdgcn_global_load_lds((const unsigned*)((const char*)(gbase) + (voff)[_i]), (PG8_LAS unsigned*)(lds + (bufoff) + ldsw + _i * 8192), 16, 0, 0); } while (0)
; #define PG8_BAR __builtin_amdgcn_s_barrier()
; template <class Epi, class Sched, bool ALIGN_EPI = false, bool SP2 = false, bool KHOOK = false>
; __device__ __forceinline__ void gemm_phase(PG8_LAS unsigned char* lds, const Gemm g, const Sched& S, const Epi& E, const int tid_in) {
;     ...
;         const char* nA = has_next ? (const char*)g.A + (size_t)nxt.pm * tstep + (size_t)nxt.pn * ksl : cA; const char* nB = has_next ? (const char*)g.Bt + (size_t)nxt.pn * bts + (size_t)nxt.pn * ksl + (gdv ? (size_t)(nxt.pm / gdv) * gst : 0) : cB;
;         GPROBE_END(2); GPROBE_BEGIN(1);
;         for (int t = 0; t < nt; t += 2) {
;             const bool last = (t == nt - 2);
;             const char* a1 = cA + (size_t)(t + 1) * kstep;
;             const char* a2 = last ? nA : cA + (size_t)(t + 2) * kstep; const char* b2 = last ? nB : cB + (size_t)(t + 2) * kstep;
;             const char* a3 = a2 + kstep; const char* b3 = b2 + kstep;
;             if (last && has_next) S.a_ready(nxt);
;             if constexpr (SP2) {
;             PG8_LDB(B0, 0, 0); PG8_LDB(B1, 0, 1); PG8_SCHED; PG8_LDA(At, 0, 0); PG8_STAGE(PG8_SA(1, 1), a1 + hstep, voffA);
;             PG8_WAIT_V(8); PG8_WAIT_L(0); PG8_BAR; PG8_MMA(0, 0, At, B0); PG8_MMA(0, 1, At, B1); PG8_BAR; PG8_SCHED;
;             PG8_LDA(At, 0, 1); PG8_STAGE(PG8_SB(0, 0), b2, voffB); PG8_STAGE(PG8_SB(0, 1), b2 + hstep, voffB); PG8_STAGE(PG8_SA(0, 0), a2, voffA);
;             PG8_WAIT_V(8); PG8_WAIT_L(0); PG8_BAR; PG8_MMA(1, 0, At, B0); PG8_MMA(1, 1, At, B1); PG8_BAR; PG8_SCHED;
.LBB0_262:
	s_ashr_i32 s17, s16, 31
	s_lshl_b64 s[18:19], s[16:17], 20
	s_add_u32 s26, s78, s18
	s_addc_u32 s27, s79, s19
	s_and_b64 s[18:19], s[22:23], exec
	s_cselect_b32 s11, s27, s49
	s_cselect_b32 s17, s26, s48
	s_ashr_i32 s15, s14, 31
	s_lshl_b64 s[18:19], s[14:15], 20
	v_readlane_b32 s5, v255, 25
	s_add_u32 s30, s5, s18
	v_readlane_b32 s5, v255, 26
	s_addc_u32 s31, s5, s19
	s_and_b64 s[18:19], s[22:23], exec
	s_cselect_b32 s15, s31, s53
	s_cselect_b32 s18, s30, s52
	s_add_u32 s48, s48, 0x80080
	s_addc_u32 s49, s49, 0
	s_add_u32 s19, s52, 0x100
	s_addc_u32 s42, s53, 0
	s_mov_b32 s44, -2
	s_add_u32 s45, s48, 0xfff80080
	s_addc_u32 s46, s49, -1
	s_add_i32 s47, 0, 0x10000
	s_cmp_eq_u32 s44, 28
	s_cselect_b32 s57, s11, s46
	s_cselect_b32 s56, s17, s45
	s_cselect_b32 s53, s15, s42
	s_cselect_b32 s52, s18, s19
	s_add_i32 s45, 0, 0x14000
	v_add_u32_e32 v156, s47, v141
	v_add_u32_e32 v172, s45, v141
	ds_read_b128 v[144:147], v156
	ds_read_b128 v[148:151], v156 offset:1024
	ds_read_b128 v[152:155], v156 offset:2048
	ds_read_b128 v[156:159], v156 offset:3072
	ds_read_b128 v[160:163], v172
	ds_read_b128 v[164:167], v172 offset:1024
	ds_read_b128 v[168:171], v172 offset:2048
	ds_read_b128 v[172:175], v172 offset:3072
	v_lshl_add_u64 v[192:193], s[48:49], 0, v[136:137]
	s_add_i32 m0, s13, 0xc000
	ds_read_b128 v[176:179], v143
	ds_read_b128 v[180:183], v143 offset:1024
	ds_read_b128 v[184:187], v143 offset:2048
	ds_read_b128 v[188:191], v143 offset:3072
	ds_read_b128 v[198:201], v143 offset:4096
	ds_read_b128 v[202:205], v143 offset:5120
	ds_read_b128 v[206:209], v143 offset:6144
	ds_read_b128 v[210:213], v143 offset:7168
	global_load_lds_dwordx4 v[192:193], off
	v_lshl_add_u64 v[192:193], s[48:49], 0, v[138:139]
	s_add_i32 m0, s13, 0xe000
	s_nop 0
	global_load_lds_dwordx4 v[192:193], off
	s_waitcnt vmcnt(18)
	s_waitcnt lgkmcnt(0)
	s_barrier
	s_setprio 1
	s_waitcnt lgkmcnt(0)
	v_mfma_f32_16x16x32_bf16 v[126:129], v[144:147], v[176:179], 0
	v_mfma_f32_16x16x32_bf16 v[122:125], v[152:155], v[176:179], 0
	v_mfma_f32_16x16x32_bf16 v[118:121], v[144:147], v[184:187], 0
	v_mfma_f32_16x16x32_bf16 v[114:117], v[152:155], v[184:187], 0
	v_mfma_f32_16x16x32_bf16 v[102:105], v[144:147], v[198:201], 0
	v_mfma_f32_16x16x32_bf16 v[98:101], v[152:155], v[198:201], 0
	v_mfma_f32_16x16x32_bf16 v[86:89], v[144:147], v[206:209], 0
	v_mfma_f32_16x16x32_bf16 v[82:85], v[152:155], v[206:209], 0
	v_mfma_f32_16x16x32_bf16 v[126:129], v[148:151], v[180:183], v[126:129]
	v_mfma_f32_16x16x32_bf16 v[122:125], v[156:159], v[180:183], v[122:125]
	v_mfma_f32_16x16x32_bf16 v[118:121], v[148:151], v[188:191], v[118:121]
	v_mfma_f32_16x16x32_bf16 v[114:117], v[156:159], v[188:191], v[114:117]
	v_mfma_f32_16x16x32_bf16 v[102:105], v[148:151], v[202:205], v[102:105]
	v_mfma_f32_16x16x32_bf16 v[98:101], v[156:159], v[202:205], v[98:101]
	v_mfma_f32_16x16x32_bf16 v[86:89], v[148:151], v[210:213], v[86:89]
	v_mfma_f32_16x16x32_bf16 v[82:85], v[156:159], v[210:213], v[82:85]
	s_setprio 0
	s_setprio 1
	v_mfma_f32_16x16x32_bf16 v[110:113], v[160:163], v[176:179], 0
	v_mfma_f32_16x16x32_bf16 v[106:109], v[168:171], v[176:179], 0
	v_mfma_f32_16x16x32_bf16 v[94:97], v[160:163], v[184:187], 0
	v_mfma_f32_16x16x32_bf16 v[90:93], v[168:171], v[184:187], 0
	v_mfma_f32_16x16x32_bf16 v[78:81], v[160:163], v[198:201], 0
	v_mfma_f32_16x16x32_bf16 v[74:77], v[168:171], v[198:201], 0
	v_mfma_f32_16x16x32_bf16 v[70:73], v[160:163], v[206:209], 0
	v_mfma_f32_16x16x32_bf16 v[66:69], v[168:171], v[206:209], 0
	v_mfma_f32_16x16x32_bf16 v[110:113], v[164:167], v[180:183], v[110:113]
	v_mfma_f32_16x16x32_bf16 v[106:109], v[172:175], v[180:183], v[106:109]
	v_mfma_f32_16x16x32_bf16 v[94:97], v[164:167], v[188:191], v[94:97]
	v_mfma_f32_16x16x32_bf16 v[90:93], v[172:175], v[188:191], v[90:93]
	v_mfma_f32_16x16x32_bf16 v[78:81], v[164:167], v[202:205], v[78:81]
	v_mfma_f32_16x16x32_bf16 v[74:77], v[172:175], v[202:205], v[74:77]
	v_mfma_f32_16x16x32_bf16 v[70:73], v[164:167], v[210:213], v[70:73]
	v_mfma_f32_16x16x32_bf16 v[66:69], v[172:175], v[210:213], v[66:69]
	s_setprio 0
	s_barrier
	s_add_i32 s46, s47, s37
	v_lshl_add_u64 v[192:193], s[52:53], 0, v[32:33]
	s_mov_b32 m0, s46
	ds_read_b128 v[176:179], v143 offset:16384
	ds_read_b128 v[180:183], v143 offset:17408
	ds_read_b128 v[184:187], v143 offset:18432
	ds_read_b128 v[188:191], v143 offset:19456
	ds_read_b128 v[198:201], v143 offset:20480
	ds_read_b128 v[202:205], v143 offset:21504
	ds_read_b128 v[206:209], v143 offset:22528
	ds_read_b128 v[210:213], v143 offset:23552
	global_load_lds_dwordx4 v[192:193], off
	s_add_i32 m0, s46, 0x2000
	s_add_u32 s46, s52, 0x80000
	v_lshl_add_u64 v[214:215], s[52:53], 0, v[134:135]
	s_addc_u32 s47, s53, 0
	s_add_i32 s45, s45, s37
	global_load_lds_dwordx4 v[214:215], off
	v_lshl_add_u64 v[216:217], s[46:47], 0, v[32:33]
	s_mov_b32 m0, s45
	v_lshl_add_u64 v[218:219], s[56:57], 0, v[132:133]
	global_load_lds_dwordx4 v[216:217], off
	v_lshl_add_u64 v[216:217], s[46:47], 0, v[134:135]
	s_add_i32 m0, s45, 0x2000
	s_nop 0
	global_load_lds_dwordx4 v[216:217], off
	v_lshl_add_u64 v[216:217], s[56:57], 0, v[130:131]
	s_mov_b32 m0, s13
	s_nop 0
	global_load_lds_dwordx4 v[216:217], off
	s_mov_b32 m0, s24
	s_nop 0
	global_load_lds_dwordx4 v[218:219], off
	s_waitcnt vmcnt(24)
	s_waitcnt lgkmcnt(0)
	s_barrier
; #define PG8_STAGE(bufoff, gbase, voff) do { _Pragma("unroll") for (int _i = 0; _i < 2; ++_i) \
;         __builtin_amdgcn_global_load_lds((const unsigned*)((const char*)(gbase) + (voff)[_i]), (PG8_LAS unsigned*)(lds + (bufoff) + ldsw + _i * 8192), 16, 0, 0); } while (0)
; #define PG8_LDA(dst, b, h) do { _Pragma("unroll") for (int m = 0; m < 4; ++m) _Pragma("unroll") for (int k = 0; k < 2; ++k) dst[m][k] = *(const PG8_LAS bf16x8*)(lds + PG8_SA(b, h) + aoff + m * 2048 + k * 1024); } while (0)
; #define PG8_LDB(dst, b, h) do { _Pragma("unroll") for (int n = 0; n < 2; ++n) _Pragma("unroll") for (int k = 0; k < 2; ++k) dst[n][k] = *(const PG8_LAS bf16x8*)(lds + PG8_SB(b, h) + boff + n * 2048 + k * 1024); } while (0)
; #define PG8_MMA(ai, bj, At, Bt) do { __builtin_amdgcn_s_setprio(1); _Pragma("unroll") for (int m = 0; m < 4; ++m) _Pragma("unroll") for (int n = 0; n < 2; ++n) _Pragma("unroll") for (int k = 0; k < 2; ++k) \
;         acc[ai][bj][m][n] = __builtin_amdgcn_mfma_f32_16x16x32_bf16(Bt[n][k], At[m][k], acc[ai][bj][m][n], 0, 0, 0); __builtin_amdgcn_s_setprio(0); } while (0)
; #define PG8_WAIT_V(n) asm volatile("s_waitcnt vmcnt(" #n ")" ::: "memory")
; #define PG8_WAIT_L(n) asm volatile("s_waitcnt lgkmcnt(" #n ")" ::: "memory")
; #define PG8_BAR __builtin_amdgcn_s_barrier()
; #define PG8_SCHED __builtin_amdgcn_sched_barrier(0)
; template <class Epi, class Sched, bool ALIGN_EPI = false, bool SP2 = false, bool KHOOK = false>
; __device__ __forceinline__ void gemm_phase(PG8_LAS unsigned char* lds, const Gemm g, const Sched& S, const Epi& E, const int tid_in) {
;     ...
;             PG8_WAIT_V(8); PG8_WAIT_L(0); PG8_BAR; PG8_MMA(1, 0, At, B0); PG8_MMA(1, 1, At, B1); PG8_BAR; PG8_SCHED;
;             PG8_LDB(B0, 1, 0); PG8_LDB(B1, 1, 1); PG8_SCHED; PG8_LDA(At, 1, 0); PG8_STAGE(PG8_SA(0, 1), a2 + hstep, voffA);
;             PG8_WAIT_V(8); PG8_WAIT_L(0); PG8_BAR; PG8_MMA(0, 0, At, B0); PG8_MMA(0, 1, At, B1); PG8_BAR; PG8_SCHED;
	s_setprio 1
	s_waitcnt lgkmcnt(0)
	v_mfma_f32_16x16x32_bf16 v[62:65], v[144:147], v[176:179], 0
	v_mfma_f32_16x16x32_bf16 v[58:61], v[152:155], v[176:179], 0
	v_mfma_f32_16x16x32_bf16 v[54:57], v[144:147], v[184:187], 0
	v_mfma_f32_16x16x32_bf16 v[50:53], v[152:155], v[184:187], 0
	v_mfma_f32_16x16x32_bf16 v[38:41], v[144:147], v[198:201], 0
	v_mfma_f32_16x16x32_bf16 v[34:37], v[152:155], v[198:201], 0
	v_mfma_f32_16x16x32_bf16 v[20:23], v[144:147], v[206:209], 0
	v_mfma_f32_16x16x32_bf16 v[16:19], v[152:155], v[206:209], 0
	v_mfma_f32_16x16x32_bf16 v[62:65], v[148:151], v[180:183], v[62:65]
	v_mfma_f32_16x16x32_bf16 v[58:61], v[156:159], v[180:183], v[58:61]
	v_mfma_f32_16x16x32_bf16 v[54:57], v[148:151], v[188:191], v[54:57]
	v_mfma_f32_16x16x32_bf16 v[50:53], v[156:159], v[188:191], v[50:53]
	v_mfma_f32_16x16x32_bf16 v[38:41], v[148:151], v[202:205], v[38:41]
	v_mfma_f32_16x16x32_bf16 v[34:37], v[156:159], v[202:205], v[34:37]
	v_mfma_f32_16x16x32_bf16 v[20:23], v[148:151], v[210:213], v[20:23]
	v_mfma_f32_16x16x32_bf16 v[16:19], v[156:159], v[210:213], v[16:19]
	s_setprio 0
	s_setprio 1
	v_mfma_f32_16x16x32_bf16 v[46:49], v[160:163], v[176:179], 0
	v_mfma_f32_16x16x32_bf16 v[42:45], v[168:171], v[176:179], 0
	v_mfma_f32_16x16x32_bf16 v[28:31], v[160:163], v[184:187], 0
	v_mfma_f32_16x16x32_bf16 v[24:27], v[168:171], v[184:187], 0
	v_mfma_f32_16x16x32_bf16 v[12:15], v[160:163], v[198:201], 0
	v_mfma_f32_16x16x32_bf16 v[8:11], v[168:171], v[198:201], 0
	v_mfma_f32_16x16x32_bf16 v[4:7], v[160:163], v[206:209], 0
	v_mfma_f32_16x16x32_bf16 v[0:3], v[168:171], v[206:209], 0
	v_mfma_f32_16x16x32_bf16 v[46:49], v[164:167], v[180:183], v[46:49]
	v_mfma_f32_16x16x32_bf16 v[42:45], v[172:175], v[180:183], v[42:45]
	v_mfma_f32_16x16x32_bf16 v[28:31], v[164:167], v[188:191], v[28:31]
	v_mfma_f32_16x16x32_bf16 v[24:27], v[172:175], v[188:191], v[24:27]
	v_mfma_f32_16x16x32_bf16 v[12:15], v[164:167], v[202:205], v[12:15]
	v_mfma_f32_16x16x32_bf16 v[8:11], v[172:175], v[202:205], v[8:11]
	v_mfma_f32_16x16x32_bf16 v[4:7], v[164:167], v[210:213], v[4:7]
	v_mfma_f32_16x16x32_bf16 v[0:3], v[172:175], v[210:213], v[0:3]
	s_setprio 0
	s_barrier
	s_add_i32 s45, 0, 0x18000
	s_add_i32 s50, 0, 0x1c000
	v_add_u32_e32 v156, s45, v141
	v_add_u32_e32 v172, s50, v141
	ds_read_b128 v[144:147], v156
	ds_read_b128 v[148:151], v156 offset:1024
	ds_read_b128 v[152:155], v156 offset:2048
	ds_read_b128 v[156:159], v156 offset:3072
	ds_read_b128 v[160:163], v172
	ds_read_b128 v[164:167], v172 offset:1024
	ds_read_b128 v[168:171], v172 offset:2048
	ds_read_b128 v[172:175], v172 offset:3072
	s_add_u32 s46, s56, 0x80000
	s_addc_u32 s47, s57, 0
	s_mov_b32 m0, s25
	v_lshl_add_u64 v[220:221], s[46:47], 0, v[130:131]
	ds_read_b128 v[176:179], v143 offset:32768
	ds_read_b128 v[180:183], v143 offset:33792
	ds_read_b128 v[184:187], v143 offset:34816
	ds_read_b128 v[188:191], v143 offset:35840
	ds_read_b128 v[198:201], v143 offset:36864
	ds_read_b128 v[202:205], v143 offset:37888
	ds_read_b128 v[206:209], v143 offset:38912
	ds_read_b128 v[210:213], v143 offset:39936
	global_load_lds_dwordx4 v[220:221], off
	v_lshl_add_u64 v[220:221], s[46:47], 0, v[132:133]
	s_mov_b32 m0, s38
	s_nop 0
	global_load_lds_dwordx4 v[220:221], off
	s_waitcnt vmcnt(8)
	s_waitcnt lgkmcnt(0)
	s_barrier
	s_setprio 1
	s_waitcnt lgkmcnt(0)
	v_mfma_f32_16x16x32_bf16 v[126:129], v[144:147], v[176:179], v[126:129]
	v_mfma_f32_16x16x32_bf16 v[122:125], v[152:155], v[176:179], v[122:125]
	v_mfma_f32_16x16x32_bf16 v[118:121], v[144:147], v[184:187], v[118:121]
	v_mfma_f32_16x16x32_bf16 v[114:117], v[152:155], v[184:187], v[114:117]
	v_mfma_f32_16x16x32_bf16 v[102:105], v[144:147], v[198:201], v[102:105]
	v_mfma_f32_16x16x32_bf16 v[98:101], v[152:155], v[198:201], v[98:101]
	v_mfma_f32_16x16x32_bf16 v[86:89], v[144:147], v[206:209], v[86:89]
	v_mfma_f32_16x16x32_bf16 v[82:85], v[152:155], v[206:209], v[82:85]
	v_mfma_f32_16x16x32_bf16 v[126:129], v[148:151], v[180:183], v[126:129]
	v_mfma_f32_16x16x32_bf16 v[122:125], v[156:159], v[180:183], v[122:125]
	v_mfma_f32_16x16x32_bf16 v[118:121], v[148:151], v[188:191], v[118:121]
	v_mfma_f32_16x16x32_bf16 v[114:117], v[156:159], v[188:191], v[114:117]
	v_mfma_f32_16x16x32_bf16 v[102:105], v[148:151], v[202:205], v[102:105]
	v_mfma_f32_16x16x32_bf16 v[98:101], v[156:159], v[202:205], v[98:101]
	v_mfma_f32_16x16x32_bf16 v[86:89], v[148:151], v[210:213], v[86:89]
	v_mfma_f32_16x16x32_bf16 v[82:85], v[156:159], v[210:213], v[82:85]
	s_setprio 0
	s_setprio 1
	v_mfma_f32_16x16x32_bf16 v[110:113], v[160:163], v[176:179], v[110:113]
	v_mfma_f32_16x16x32_bf16 v[106:109], v[168:171], v[176:179], v[106:109]
	v_mfma_f32_16x16x32_bf16 v[94:97], v[160:163], v[184:187], v[94:97]
	v_mfma_f32_16x16x32_bf16 v[90:93], v[168:171], v[184:187], v[90:93]
	v_mfma_f32_16x16x32_bf16 v[78:81], v[160:163], v[198:201], v[78:81]
	v_mfma_f32_16x16x32_bf16 v[74:77], v[168:171], v[198:201], v[74:77]
	v_mfma_f32_16x16x32_bf16 v[70:73], v[160:163], v[206:209], v[70:73]
	v_mfma_f32_16x16x32_bf16 v[66:69], v[168:171], v[206:209], v[66:69]
	v_mfma_f32_16x16x32_bf16 v[110:113], v[164:167], v[180:183], v[110:113]
	v_mfma_f32_16x16x32_bf16 v[106:109], v[172:175], v[180:183], v[106:109]
	v_mfma_f32_16x16x32_bf16 v[94:97], v[164:167], v[188:191], v[94:97]
	v_mfma_f32_16x16x32_bf16 v[90:93], v[172:175], v[188:191], v[90:93]
	v_mfma_f32_16x16x32_bf16 v[78:81], v[164:167], v[202:205], v[78:81]
	v_mfma_f32_16x16x32_bf16 v[74:77], v[172:175], v[202:205], v[74:77]
	v_mfma_f32_16x16x32_bf16 v[70:73], v[164:167], v[210:213], v[70:73]
	v_mfma_f32_16x16x32_bf16 v[66:69], v[172:175], v[210:213], v[66:69]
	s_setprio 0
	s_barrier
; #define PG8_STAGE(bufoff, gbase, voff) do { _Pragma("unroll") for (int _i = 0; _i < 2; ++_i) \
;         __builtin_amdgcn_global_load_lds((const unsigned*)((const char*)(gbase) + (voff)[_i]), (PG8_LAS unsigned*)(lds + (bufoff) + ldsw + _i * 8192), 16, 0, 0); } while (0)
; #define PG8_LDA(dst, b, h) do { _Pragma("unroll") for (int m = 0; m < 4; ++m) _Pragma("unroll") for (int k = 0; k < 2; ++k) dst[m][k] = *(const PG8_LAS bf16x8*)(lds + PG8_SA(b, h) + aoff + m * 2048 + k * 1024); } while (0)
; #define PG8_MMA(ai, bj, At, Bt) do { __builtin_amdgcn_s_setprio(1); _Pragma("unroll") for (int m = 0; m < 4; ++m) _Pragma("unroll") for (int n = 0; n < 2; ++n) _Pragma("unroll") for (int k = 0; k < 2; ++k) \
;         acc[ai][bj][m][n] = __builtin_amdgcn_mfma_f32_16x16x32_bf16(Bt[n][k], At[m][k], acc[ai][bj][m][n], 0, 0, 0); __builtin_amdgcn_s_setprio(0); } while (0)
; #define PG8_WAIT_V(n) asm volatile("s_waitcnt vmcnt(" #n ")" ::: "memory")
; #define PG8_WAIT_L(n) asm volatile("s_waitcnt lgkmcnt(" #n ")" ::: "memory")
; #define PG8_BAR __builtin_amdgcn_s_barrier()
; #define PG8_SCHED __builtin_amdgcn_sched_barrier(0)
; template <class Epi, class Sched, bool ALIGN_EPI = false, bool SP2 = false, bool KHOOK = false>
; __device__ __forceinline__ void gemm_phase(PG8_LAS unsigned char* lds, const Gemm g, const Sched& S, const Epi& E, const int tid_in) {
;     ...
;         for (int t = 0; t < nt; t += 2) {
;             const bool last = (t == nt - 2);
;             const char* a1 = cA + (size_t)(t + 1) * kstep;
;             const char* a2 = last ? nA : cA + (size_t)(t + 2) * kstep; const char* b2 = last ? nB : cB + (size_t)(t + 2) * kstep;
;     ...
;             PG8_LDA(At, 1, 1); PG8_STAGE(PG8_SB(1, 0), b3, voffB); PG8_STAGE(PG8_SB(1, 1), b3 + hstep, voffB); PG8_STAGE(PG8_SA(1, 0), a3, voffA);
;             PG8_WAIT_V(8); PG8_WAIT_L(0); PG8_BAR; PG8_MMA(1, 0, At, B0); PG8_MMA(1, 1, At, B1); PG8_BAR; PG8_SCHED;
	s_add_i32 s45, s45, s37
	v_lshl_add_u64 v[192:193], v[192:193], 0, s[90:91]
	s_mov_b32 m0, s45
	ds_read_b128 v[176:179], v143 offset:49152
	ds_read_b128 v[180:183], v143 offset:50176
	ds_read_b128 v[184:187], v143 offset:51200
	ds_read_b128 v[188:191], v143 offset:52224
	ds_read_b128 v[198:201], v143 offset:53248
	ds_read_b128 v[202:205], v143 offset:54272
	ds_read_b128 v[206:209], v143 offset:55296
	ds_read_b128 v[210:213], v143 offset:56320
	global_load_lds_dwordx4 v[192:193], off
	s_add_i32 m0, s45, 0x2000
	s_add_u32 s46, s52, 0x80080
	v_lshl_add_u64 v[192:193], v[214:215], 0, s[90:91]
	s_addc_u32 s47, s53, 0
	s_add_i32 s45, s50, s37
	global_load_lds_dwordx4 v[192:193], off
	v_lshl_add_u64 v[192:193], s[46:47], 0, v[32:33]
	s_mov_b32 m0, s45
	s_nop 0
	global_load_lds_dwordx4 v[192:193], off
	v_lshl_add_u64 v[192:193], s[46:47], 0, v[134:135]
	s_add_i32 m0, s45, 0x2000
	s_nop 0
	global_load_lds_dwordx4 v[192:193], off
	v_lshl_add_u64 v[192:193], v[216:217], 0, s[90:91]
	s_mov_b32 m0, s39
	s_nop 0
	global_load_lds_dwordx4 v[192:193], off
	v_lshl_add_u64 v[192:193], v[218:219], 0, s[90:91]
	s_mov_b32 m0, s40
	s_nop 0
	global_load_lds_dwordx4 v[192:193], off
	s_waitcnt vmcnt(8)
	s_waitcnt lgkmcnt(0)
	s_barrier
	s_setprio 1
	s_waitcnt lgkmcnt(0)
	v_mfma_f32_16x16x32_bf16 v[62:65], v[144:147], v[176:179], v[62:65]
	v_mfma_f32_16x16x32_bf16 v[58:61], v[152:155], v[176:179], v[58:61]
	v_mfma_f32_16x16x32_bf16 v[54:57], v[144:147], v[184:187], v[54:57]
	v_mfma_f32_16x16x32_bf16 v[50:53], v[152:155], v[184:187], v[50:53]
	v_mfma_f32_16x16x32_bf16 v[38:41], v[144:147], v[198:201], v[38:41]
	v_mfma_f32_16x16x32_bf16 v[34:37], v[152:155], v[198:201], v[34:37]
	v_mfma_f32_16x16x32_bf16 v[20:23], v[144:147], v[206:209], v[20:23]
	v_mfma_f32_16x16x32_bf16 v[16:19], v[152:155], v[206:209], v[16:19]
	v_mfma_f32_16x16x32_bf16 v[62:65], v[148:151], v[180:183], v[62:65]
	v_mfma_f32_16x16x32_bf16 v[58:61], v[156:159], v[180:183], v[58:61]
	v_mfma_f32_16x16x32_bf16 v[54:57], v[148:151], v[188:191], v[54:57]
	v_mfma_f32_16x16x32_bf16 v[50:53], v[156:159], v[188:191], v[50:53]
	v_mfma_f32_16x16x32_bf16 v[38:41], v[148:151], v[202:205], v[38:41]
	v_mfma_f32_16x16x32_bf16 v[34:37], v[156:159], v[202:205], v[34:37]
	v_mfma_f32_16x16x32_bf16 v[20:23], v[148:151], v[210:213], v[20:23]
	v_mfma_f32_16x16x32_bf16 v[16:19], v[156:159], v[210:213], v[16:19]
	s_setprio 0
	s_setprio 1
	v_mfma_f32_16x16x32_bf16 v[46:49], v[160:163], v[176:179], v[46:49]
	v_mfma_f32_16x16x32_bf16 v[42:45], v[168:171], v[176:179], v[42:45]
	v_mfma_f32_16x16x32_bf16 v[28:31], v[160:163], v[184:187], v[28:31]
	v_mfma_f32_16x16x32_bf16 v[24:27], v[168:171], v[184:187], v[24:27]
	v_mfma_f32_16x16x32_bf16 v[12:15], v[160:163], v[198:201], v[12:15]
	v_mfma_f32_16x16x32_bf16 v[8:11], v[168:171], v[198:201], v[8:11]
	v_mfma_f32_16x16x32_bf16 v[4:7], v[160:163], v[206:209], v[4:7]
	v_mfma_f32_16x16x32_bf16 v[0:3], v[168:171], v[206:209], v[0:3]
	v_mfma_f32_16x16x32_bf16 v[46:49], v[164:167], v[180:183], v[46:49]
	v_mfma_f32_16x16x32_bf16 v[42:45], v[172:175], v[180:183], v[42:45]
	v_mfma_f32_16x16x32_bf16 v[28:31], v[164:167], v[188:191], v[28:31]
	v_mfma_f32_16x16x32_bf16 v[24:27], v[172:175], v[188:191], v[24:27]
	v_mfma_f32_16x16x32_bf16 v[12:15], v[164:167], v[202:205], v[12:15]
	v_mfma_f32_16x16x32_bf16 v[8:11], v[172:175], v[202:205], v[8:11]
	v_mfma_f32_16x16x32_bf16 v[4:7], v[164:167], v[210:213], v[4:7]
	v_mfma_f32_16x16x32_bf16 v[0:3], v[172:175], v[210:213], v[0:3]
	s_setprio 0
	s_barrier
	s_add_i32 s44, s44, 2
	s_add_u32 s48, s48, 0x100
	s_addc_u32 s49, s49, 0
	s_add_u32 s19, s19, 0x100
	s_addc_u32 s42, s42, 0
	s_cmp_gt_u32 s44, 29

; #define PG8_STAGE(bufoff, gbase, voff) do { _Pragma("unroll") for (int _i = 0; _i < 2; ++_i) \
;         __builtin_amdgcn_global_load_lds((const unsigned*)((const char*)(gbase) + (voff)[_i]), (PG8_LAS unsigned*)(lds + (bufoff) + ldsw + _i * 8192), 16, 0, 0); } while (0)
; #define PG8_WAIT_V(n) asm volatile("s_waitcnt vmcnt(" #n ")" ::: "memory")
; #define PG8_BAR __builtin_amdgcn_s_barrier()
; template <class Epi, class Sched, bool ALIGN_EPI = false, bool SP2 = false, bool KHOOK = false>
; __device__ __forceinline__ void gemm_phase(PG8_LAS unsigned char* lds, const Gemm g, const Sched& S, const Epi& E, const int tid_in) {
;     ...
;     if constexpr (SP2) {
;         PG8_STAGE(PG8_SB(0, 0), cB, voffB); PG8_STAGE(PG8_SB(0, 1), cB + hstep, voffB); PG8_STAGE(PG8_SA(0, 0), cA, voffA); PG8_STAGE(PG8_SA(0, 1), cA + hstep, voffA);
;         if (wr == 1) PG8_BAR;
;         PG8_WAIT_V(2); PG8_BAR;
;         PG8_STAGE(PG8_SB(1, 0), cB + kstep, voffB); PG8_STAGE(PG8_SA(1, 0), cA + kstep, voffA); PG8_STAGE(PG8_SB(1, 1), cB + hstep + kstep, voffB);
;         PG8_WAIT_V(6); PG8_BAR;
.LBB0_406:
	v_lshl_add_u64 v[2:3], s[30:31], 0, v[32:33]
	v_mov_b32_e32 v67, v33
	v_readlane_b32 s52, v253, 44
	v_lshl_add_u64 v[4:5], s[30:31], 0, v[66:67]
	v_readlane_b32 s53, v253, 45
	s_and_b32 s8, s6, 3
	s_add_i32 m0, s20, 0x18000
	v_lshl_add_u64 v[2:3], v[2:3], 0, s[90:91]
	v_lshl_add_u64 v[6:7], s[52:53], 0, v[32:33]
	s_lshl_b32 s9, s5, 13
	s_lshl_b32 s10, s8, 12
	global_load_lds_dwordx4 v[2:3], off
	v_lshl_add_u64 v[2:3], v[4:5], 0, s[90:91]
	s_add_i32 m0, s20, 0x1a000
	s_add_i32 s38, s20, 0x8000
	s_add_i32 s39, s20, 0xa000
	v_lshl_add_u64 v[8:9], s[52:53], 0, v[66:67]
	global_load_lds_dwordx4 v[2:3], off
	v_lshl_add_u64 v[2:3], v[6:7], 0, s[90:91]
	s_mov_b32 m0, s38
	s_add_u32 s6, s30, 0x80080
	global_load_lds_dwordx4 v[2:3], off
	v_lshl_add_u64 v[2:3], v[8:9], 0, s[90:91]
	s_mov_b32 m0, s39
	s_addc_u32 s7, s31, 0
	s_add_i32 s40, s20, 0x1c000
	global_load_lds_dwordx4 v[2:3], off
	v_lshl_add_u64 v[2:3], s[6:7], 0, v[32:33]
	s_mov_b32 m0, s40
	s_add_i32 s41, s20, 0x1e000
	global_load_lds_dwordx4 v[2:3], off
	v_lshl_add_u64 v[2:3], s[6:7], 0, v[66:67]
	s_mov_b32 m0, s41
	v_and_b32_e32 v1, 15, v0
	global_load_lds_dwordx4 v[2:3], off
	s_waitcnt vmcnt(2)
	s_barrier
	v_and_b32_e32 v2, 48, v0
	v_lshlrev_b32_e32 v0, 2, v0
	v_lshl_or_b32 v70, s5, 6, v1
	v_lshl_or_b32 v1, v1, 6, v2
	v_and_b32_e32 v0, 32, v0
	s_cmpk_lt_u32 s4, 0x100
	v_bitop3_b32 v3, v1, s9, v0 bitop3:0xde
	v_bitop3_b32 v71, v1, s10, v0 bitop3:0xde
	s_cselect_b64 s[4:5], -1, 0
	s_cmp_lt_u32 s8, 2
	v_lshl_or_b32 v0, s8, 7, v2
	v_readlane_b32 s8, v253, 1
	s_waitcnt vmcnt(6)
	v_mov_b32_e32 v1, v33
	v_readlane_b32 s9, v253, 2
	v_readlane_b32 s10, v254, 18
	v_readlane_b32 s16, v253, 57
	v_lshl_add_u64 v[68:69], s[8:9], 0, v[0:1]
	v_readlane_b32 s8, v254, 40
	s_cselect_b64 s[6:7], -1, 0
	v_mov_b32_e32 v73, 0x7ffffffe
	v_add_u32_e32 v72, 0, v3
	v_readlane_b32 s9, v254, 41
	s_mov_b32 s15, s10
	s_mov_b32 s14, s16
	s_barrier
	v_readlane_b32 s11, v254, 19
	v_readlane_b32 s17, v253, 58
	s_branch .LBB0_409

; #define PG8_STAGE(bufoff, gbase, voff) do { _Pragma("unroll") for (int _i = 0; _i < 2; ++_i) \
;         __builtin_amdgcn_global_load_lds((const unsigned*)((const char*)(gbase) + (voff)[_i]), (PG8_LAS unsigned*)(lds + (bufoff) + ldsw + _i * 8192), 16, 0, 0); } while (0)
; #define PG8_WAIT_V(n) asm volatile("s_waitcnt vmcnt(" #n ")" ::: "memory")
; #define PG8_BAR __builtin_amdgcn_s_barrier()
; template <class Epi, class Sched, bool ALIGN_EPI = false, bool SP2 = false, bool KHOOK = false>
; __device__ __forceinline__ void gemm_phase(PG8_LAS unsigned char* lds, const Gemm g, const Sched& S, const Epi& E, const int tid_in) {
;     ...
;     if constexpr (SP2) {
;         PG8_STAGE(PG8_SB(0, 0), cB, voffB); PG8_STAGE(PG8_SB(0, 1), cB + hstep, voffB); PG8_STAGE(PG8_SA(0, 0), cA, voffA); PG8_STAGE(PG8_SA(0, 1), cA + hstep, voffA);
;         if (wr == 1) PG8_BAR;
;         PG8_WAIT_V(2); PG8_BAR;
;         PG8_STAGE(PG8_SB(1, 0), cB + kstep, voffB); PG8_STAGE(PG8_SA(1, 0), cA + kstep, voffA); PG8_STAGE(PG8_SB(1, 1), cB + hstep + kstep, voffB);
;         PG8_WAIT_V(6); PG8_BAR;
.LBB0_832:
	v_and_b32_e32 v11, 15, v7
	v_lshrrev_b32_e32 v7, 1, v7
	v_and_b32_e32 v7, 24, v7
	v_readlane_b32 s16, v253, 53
	v_lshlrev_b32_e32 v16, 1, v7
	s_lshl_b32 s6, s6, 5
	v_mov_b32_e32 v167, v33
	v_readlane_b32 s17, v253, 54
	v_lshl_or_b32 v186, s5, 6, v11
	v_lshl_or_b32 v16, v11, 6, v16
	v_lshlrev_b32_e32 v11, 2, v11
	s_and_b32 s8, s6, 0x60
	s_add_i32 m0, s20, 0x18000
	v_lshl_add_u64 v[0:1], v[0:1], 0, s[90:91]
	v_lshl_add_u64 v[12:13], s[16:17], 0, v[166:167]
	v_mov_b32_e32 v163, v33
	s_lshl_b32 s7, s5, 13
	v_and_b32_e32 v17, 32, v11
	s_lshl_b32 s6, s8, 7
	global_load_lds_dwordx4 v[0:1], off
	v_lshl_add_u64 v[0:1], v[2:3], 0, s[90:91]
	s_add_i32 m0, s20, 0x1a000
	s_add_i32 s38, s20, 0x8000
	s_add_i32 s39, s20, 0xa000
	v_lshl_add_u64 v[14:15], s[16:17], 0, v[162:163]
	v_bitop3_b32 v187, s6, v16, v17 bitop3:0xf6
	global_load_lds_dwordx4 v[0:1], off
	v_lshl_add_u64 v[0:1], v[12:13], 0, s[90:91]
	s_mov_b32 m0, s38
	s_add_u32 s6, s26, 0x100080
	v_bitop3_b32 v18, v16, s7, v17 bitop3:0xde
	global_load_lds_dwordx4 v[0:1], off
	v_lshl_add_u64 v[0:1], v[14:15], 0, s[90:91]
	s_mov_b32 m0, s39
	s_addc_u32 s7, s27, 0
	global_load_lds_dwordx4 v[0:1], off
	s_add_i32 m0, s20, 0x1c000
	v_lshl_add_u64 v[0:1], s[6:7], 0, v[164:165]
	global_load_lds_dwordx4 v[0:1], off
	v_lshl_add_u64 v[0:1], s[6:7], 0, v[160:161]
	s_add_i32 m0, s20, 0x1e000
	s_lshl_b32 s5, s5, 8
	global_load_lds_dwordx4 v[0:1], off
	s_waitcnt vmcnt(2)
	s_barrier
	v_lshlrev_b32_e32 v0, 16, v9
	v_and_b32_e32 v0, 0xfffe0000, v0
	v_lshl_add_u32 v0, v8, 13, v0
	v_and_b32_e32 v1, 1, v9
	v_lshl_or_b32 v0, v1, 6, v0
	v_lshl_add_u32 v170, v10, 1, v0
	v_lshlrev_b32_e32 v0, 16, v4
	s_add_i32 s5, s5, 0
	v_and_b32_e32 v0, 0xfffe0000, v0
	v_readlane_b32 s10, v254, 18
	s_waitcnt vmcnt(6)
	s_add_i32 s5, s5, 0x20000
	v_readlane_b32 s6, v253, 16
	v_lshl_add_u32 v0, v5, 13, v0
	v_and_b32_e32 v1, 1, v4
	v_readlane_b32 s11, v254, 19
	v_readlane_b32 s7, v253, 17
	s_cmpk_lt_u32 s4, 0x100
	v_lshl_or_b32 v0, v1, 6, v0
	s_mov_b32 s24, s10
	v_readlane_b32 s10, v253, 57
	v_add_u32_e32 v188, s5, v11
	v_lshl_add_u64 v[168:169], s[6:7], 0, v[32:33]
	s_cselect_b64 s[4:5], -1, 0
	v_or_b32_e32 v189, s8, v7
	v_mov_b32_e32 v171, v33
	v_lshl_add_u32 v172, v6, 1, v0
	v_mov_b32_e32 v173, v33
	s_mov_b32 s40, 0
	v_add_u32_e32 v190, 0, v18
	s_mov_b32 s25, s10
	s_barrier
	v_readlane_b32 s11, v253, 58
	s_branch .LBB0_835

; #define PG8_STAGE(bufoff, gbase, voff) do { _Pragma("unroll") for (int _i = 0; _i < 2; ++_i) \
;         __builtin_amdgcn_global_load_lds((const unsigned*)((const char*)(gbase) + (voff)[_i]), (PG8_LAS unsigned*)(lds + (bufoff) + ldsw + _i * 8192), 16, 0, 0); } while (0)
; #define PG8_WAIT_V(n) asm volatile("s_waitcnt vmcnt(" #n ")" ::: "memory")
; #define PG8_BAR __builtin_amdgcn_s_barrier()
; template <class Epi, class Sched, bool ALIGN_EPI = false, bool SP2 = false, bool KHOOK = false>
; __device__ __forceinline__ void gemm_phase(PG8_LAS unsigned char* lds, const Gemm g, const Sched& S, const Epi& E, const int tid_in) {
;     ...
;     if constexpr (SP2) {
;         PG8_STAGE(PG8_SB(0, 0), cB, voffB); PG8_STAGE(PG8_SB(0, 1), cB + hstep, voffB); PG8_STAGE(PG8_SA(0, 0), cA, voffA); PG8_STAGE(PG8_SA(0, 1), cA + hstep, voffA);
;         if (wr == 1) PG8_BAR;
;         PG8_WAIT_V(2); PG8_BAR;
;         PG8_STAGE(PG8_SB(1, 0), cB + kstep, voffB); PG8_STAGE(PG8_SA(1, 0), cA + kstep, voffA); PG8_STAGE(PG8_SB(1, 1), cB + hstep + kstep, voffB);
;         PG8_WAIT_V(6); PG8_BAR;
.LBB0_856:
	v_lshrrev_b32_e32 v16, 1, v6
	v_and_b32_e32 v16, 24, v16
	s_lshl_b32 s5, s5, 5
	v_and_b32_e32 v7, 15, v6
	v_lshlrev_b32_e32 v17, 1, v16
	v_lshlrev_b32_e32 v6, 2, v6
	s_and_b32 s8, s5, 0x60
	v_lshl_add_u64 v[8:9], s[22:23], 0, v[32:33]
	v_mov_b32_e32 v203, v33
	v_readlane_b32 s16, v253, 62
	v_lshl_or_b32 v246, s6, 6, v7
	v_lshl_or_b32 v7, v7, 6, v17
	s_lshl_b32 s6, s6, 13
	v_and_b32_e32 v6, 32, v6
	s_lshl_b32 s5, s8, 7
	v_lshl_add_u64 v[10:11], s[22:23], 0, v[202:203]
	v_mov_b32_e32 v207, v33
	v_readlane_b32 s17, v253, 63
	v_bitop3_b32 v17, v7, s6, v6 bitop3:0xde
	v_bitop3_b32 v247, s5, v7, v6 bitop3:0xf6
	s_add_i32 m0, s20, 0x18000
	v_lshl_add_u64 v[6:7], v[8:9], 0, s[90:91]
	v_lshl_add_u64 v[12:13], s[16:17], 0, v[206:207]
	v_mov_b32_e32 v205, v33
	global_load_lds_dwordx4 v[6:7], off
	v_lshl_add_u64 v[6:7], v[10:11], 0, s[90:91]
	s_add_i32 m0, s20, 0x1a000
	s_add_i32 s36, s20, 0x8000
	s_add_i32 s37, s20, 0xa000
	v_lshl_add_u64 v[14:15], s[16:17], 0, v[204:205]
	global_load_lds_dwordx4 v[6:7], off
	v_lshl_add_u64 v[6:7], v[12:13], 0, s[90:91]
	s_mov_b32 m0, s36
	s_add_u32 s6, s22, 0x80080
	global_load_lds_dwordx4 v[6:7], off
	v_lshl_add_u64 v[6:7], v[14:15], 0, s[90:91]
	s_mov_b32 m0, s37
	s_addc_u32 s7, s23, 0
	global_load_lds_dwordx4 v[6:7], off
	s_add_i32 m0, s20, 0x1c000
	v_lshl_add_u64 v[6:7], s[6:7], 0, v[32:33]
	global_load_lds_dwordx4 v[6:7], off
	v_lshl_add_u64 v[6:7], s[6:7], 0, v[202:203]
	s_add_i32 m0, s20, 0x1e000
	s_cmpk_lt_u32 s4, 0x100
	global_load_lds_dwordx4 v[6:7], off
	s_waitcnt vmcnt(2)
	s_barrier
	v_lshlrev_b32_e32 v6, 15, v4
	v_and_b32_e32 v6, 0xffff0000, v6
	v_lshl_add_u32 v3, v3, 12, v6
	v_and_b32_e32 v4, 1, v4
	v_lshl_or_b32 v3, v4, 6, v3
	v_lshl_add_u32 v208, v5, 1, v3
	v_lshlrev_b32_e32 v3, 15, v0
	v_and_b32_e32 v3, 0xffff0000, v3
	s_waitcnt vmcnt(6)
	v_lshl_add_u32 v1, v1, 12, v3
	v_and_b32_e32 v0, 1, v0
	v_lshl_or_b32 v0, v0, 6, v1
	v_readlane_b32 s6, v254, 18
	v_readlane_b32 s10, v253, 57
	s_cselect_b64 s[4:5], -1, 0
	v_or_b32_e32 v248, s8, v16
	v_mov_b32_e32 v209, v33
	v_lshl_add_u32 v210, v2, 1, v0
	v_mov_b32_e32 v211, v33
	s_mov_b32 s38, 0
	v_add_u32_e32 v249, 0, v17
	s_mov_b32 s24, s6
	s_mov_b32 s25, s10
	s_barrier
	v_readlane_b32 s7, v254, 19
	v_readlane_b32 s11, v253, 58
	s_branch .LBB0_859

; #define PG8_STAGE(bufoff, gbase, voff) do { _Pragma("unroll") for (int _i = 0; _i < 2; ++_i) \
;         __builtin_amdgcn_global_load_lds((const unsigned*)((const char*)(gbase) + (voff)[_i]), (PG8_LAS unsigned*)(lds + (bufoff) + ldsw + _i * 8192), 16, 0, 0); } while (0)
; #define PG8_WAIT_V(n) asm volatile("s_waitcnt vmcnt(" #n ")" ::: "memory")
; #define PG8_BAR __builtin_amdgcn_s_barrier()
; template <class Epi, class Sched, bool ALIGN_EPI = false, bool SP2 = false, bool KHOOK = false>
; __device__ __forceinline__ void gemm_phase(PG8_LAS unsigned char* lds, const Gemm g, const Sched& S, const Epi& E, const int tid_in) {
;     ...
;     f32x4 acc[2][2][4][2];
; #pragma unroll
;     for (int a = 0; a < 2; ++a)
; #pragma unroll
;         for (int b = 0; b < 2; ++b)
; #pragma unroll
;             for (int m = 0; m < 4; ++m)
; #pragma unroll
;                 for (int n = 0; n < 2; ++n) acc[a][b][m][n] = (f32x4){0.f, 0.f, 0.f, 0.f};
;     ...
;     if constexpr (SP2) {
;         PG8_STAGE(PG8_SB(0, 0), cB, voffB); PG8_STAGE(PG8_SB(0, 1), cB + hstep, voffB); PG8_STAGE(PG8_SA(0, 0), cA, voffA); PG8_STAGE(PG8_SA(0, 1), cA + hstep, voffA);
;         if (wr == 1) PG8_BAR;
;         PG8_WAIT_V(2); PG8_BAR;
;         PG8_STAGE(PG8_SB(1, 0), cB + kstep, voffB); PG8_STAGE(PG8_SA(1, 0), cA + kstep, voffA); PG8_STAGE(PG8_SB(1, 1), cB + hstep + kstep, voffB);
;         PG8_WAIT_V(6); PG8_BAR;
.LBB0_939:
	v_lshl_add_u64 v[6:7], s[48:49], 0, v[32:33]
	v_mov_b32_e32 v123, v33
	v_readlane_b32 s14, v254, 4
	v_and_b32_e32 v174, 15, v173
	v_and_b32_e32 v14, 48, v173
	v_lshlrev_b32_e32 v15, 2, v173
	v_lshl_add_u64 v[8:9], s[48:49], 0, v[122:123]
	v_mov_b32_e32 v127, v33
	v_readlane_b32 s15, v254, 5
	s_and_b32 s36, s1, 3
	s_lshl_b32 s0, s20, 13
	v_lshl_or_b32 v14, v174, 6, v14
	v_and_b32_e32 v15, 32, v15
	s_add_i32 m0, s40, 0x18000
	v_lshl_add_u64 v[6:7], v[6:7], 0, s[90:91]
	v_lshl_add_u64 v[10:11], s[14:15], 0, v[126:127]
	v_mov_b32_e32 v125, v33
	s_lshl_b32 s45, s20, 6
	v_bitop3_b32 v16, v14, s0, v15 bitop3:0xde
	s_lshl_b32 s0, s36, 12
	global_load_lds_dwordx4 v[6:7], off
	v_lshl_add_u64 v[6:7], v[8:9], 0, s[90:91]
	s_add_i32 m0, s40, 0x1a000
	s_add_i32 s46, s40, 0x8000
	s_add_i32 s47, s40, 0xa000
	v_lshl_add_u64 v[12:13], s[14:15], 0, v[124:125]
	global_load_lds_dwordx4 v[6:7], off
	v_lshl_add_u64 v[6:7], v[10:11], 0, s[90:91]
	s_mov_b32 m0, s46
	s_add_u32 s4, s48, 0x80080
	global_load_lds_dwordx4 v[6:7], off
	v_lshl_add_u64 v[6:7], v[12:13], 0, s[90:91]
	s_mov_b32 m0, s47
	s_addc_u32 s5, s49, 0
	global_load_lds_dwordx4 v[6:7], off
	s_add_i32 m0, s40, 0x1c000
	v_lshl_add_u64 v[6:7], s[4:5], 0, v[32:33]
	global_load_lds_dwordx4 v[6:7], off
	v_lshl_add_u64 v[6:7], s[4:5], 0, v[122:123]
	s_add_i32 m0, s40, 0x1e000
	v_readlane_b32 s4, v254, 18
	global_load_lds_dwordx4 v[6:7], off
	s_waitcnt vmcnt(2)
	s_barrier
	v_lshlrev_b32_e32 v6, 15, v4
	v_and_b32_e32 v6, 0xffff0000, v6
	v_lshl_add_u32 v3, v3, 12, v6
	v_and_b32_e32 v4, 1, v4
	v_lshl_or_b32 v3, v4, 6, v3
	v_lshl_add_u32 v128, v5, 1, v3
	v_lshlrev_b32_e32 v3, 15, v0
	v_and_b32_e32 v3, 0xffff0000, v3
	v_lshl_add_u32 v1, v1, 12, v3
	v_and_b32_e32 v0, 1, v0
	v_readlane_b32 s5, v254, 19
	s_waitcnt vmcnt(6)
	v_lshl_or_b32 v0, v0, 6, v1
	s_mov_b32 s33, s4
	v_readlane_b32 s4, v253, 57
	v_lshl_add_u32 v138, v2, 1, v0
	v_mov_b32_e32 v0, 0
	v_readlane_b32 s5, v253, 58
	v_or_b32_e32 v172, s45, v174
	v_bitop3_b32 v144, s0, v14, v15 bitop3:0xf6
	v_mov_b32_e32 v129, v33
	v_mov_b32_e32 v139, v33
	s_mov_b32 s50, 0
	v_add_u32_e32 v145, 0, v16
	s_mov_b32 s0, s4
	s_mov_b64 s[4:5], s[14:15]
	v_mov_b32_e32 v1, v0
	v_mov_b32_e32 v2, v0
	v_mov_b32_e32 v3, v0
	v_mov_b32_e32 v4, v0
	v_mov_b32_e32 v5, v0
	v_mov_b32_e32 v6, v0
	v_mov_b32_e32 v7, v0
	v_mov_b32_e32 v16, v0
	v_mov_b32_e32 v17, v0
	v_mov_b32_e32 v18, v0
	v_mov_b32_e32 v19, v0
	v_mov_b32_e32 v20, v0
	v_mov_b32_e32 v21, v0
	v_mov_b32_e32 v22, v0
	v_mov_b32_e32 v23, v0
	v_mov_b32_e32 v34, v0
	v_mov_b32_e32 v35, v0
	v_mov_b32_e32 v36, v0
	v_mov_b32_e32 v37, v0
	v_mov_b32_e32 v38, v0
	v_mov_b32_e32 v39, v0
	v_mov_b32_e32 v40, v0
	v_mov_b32_e32 v41, v0
	v_mov_b32_e32 v50, v0
	v_mov_b32_e32 v51, v0
	v_mov_b32_e32 v52, v0
	v_mov_b32_e32 v53, v0
	v_mov_b32_e32 v54, v0
	v_mov_b32_e32 v55, v0
	v_mov_b32_e32 v56, v0
	v_mov_b32_e32 v57, v0
	v_mov_b32_e32 v8, v0
	v_mov_b32_e32 v9, v0
	v_mov_b32_e32 v10, v0
	v_mov_b32_e32 v11, v0
	v_mov_b32_e32 v12, v0
	v_mov_b32_e32 v13, v0
	v_mov_b32_e32 v14, v0
	v_mov_b32_e32 v15, v0
	v_mov_b32_e32 v24, v0
	v_mov_b32_e32 v25, v0
	v_mov_b32_e32 v26, v0
	v_mov_b32_e32 v27, v0
	v_mov_b32_e32 v28, v0
	v_mov_b32_e32 v29, v0
	v_mov_b32_e32 v30, v0
	v_mov_b32_e32 v31, v0
	v_mov_b32_e32 v42, v0
	v_mov_b32_e32 v43, v0
	v_mov_b32_e32 v44, v0
	v_mov_b32_e32 v45, v0
	v_mov_b32_e32 v46, v0
	v_mov_b32_e32 v47, v0
	v_mov_b32_e32 v48, v0
	v_mov_b32_e32 v49, v0
	v_mov_b32_e32 v58, v0
	v_mov_b32_e32 v59, v0
	v_mov_b32_e32 v60, v0
	v_mov_b32_e32 v61, v0
	v_mov_b32_e32 v62, v0
	v_mov_b32_e32 v63, v0
	v_mov_b32_e32 v64, v0
	v_mov_b32_e32 v65, v0
	v_mov_b32_e32 v66, v0
	v_mov_b32_e32 v67, v0
	v_mov_b32_e32 v68, v0
	v_mov_b32_e32 v69, v0
	v_mov_b32_e32 v70, v0
	v_mov_b32_e32 v71, v0
	v_mov_b32_e32 v72, v0
	v_mov_b32_e32 v73, v0
	v_mov_b32_e32 v82, v0
	v_mov_b32_e32 v83, v0
	v_mov_b32_e32 v84, v0
	v_mov_b32_e32 v85, v0
	v_mov_b32_e32 v86, v0
	v_mov_b32_e32 v87, v0
	v_mov_b32_e32 v88, v0
	v_mov_b32_e32 v89, v0
	v_mov_b32_e32 v98, v0
	v_mov_b32_e32 v99, v0
	v_mov_b32_e32 v100, v0
	v_mov_b32_e32 v101, v0
	v_mov_b32_e32 v110, v0
	v_mov_b32_e32 v111, v0
	v_mov_b32_e32 v112, v0
	v_mov_b32_e32 v113, v0
	v_mov_b32_e32 v102, v0
	v_mov_b32_e32 v103, v0
	v_mov_b32_e32 v104, v0
	v_mov_b32_e32 v105, v0
	v_mov_b32_e32 v106, v0
	v_mov_b32_e32 v107, v0
	v_mov_b32_e32 v108, v0
	v_mov_b32_e32 v109, v0
	v_mov_b32_e32 v74, v0
	v_mov_b32_e32 v75, v0
	v_mov_b32_e32 v76, v0
	v_mov_b32_e32 v77, v0
	v_mov_b32_e32 v78, v0
	v_mov_b32_e32 v79, v0
	v_mov_b32_e32 v80, v0
	v_mov_b32_e32 v81, v0
	v_mov_b32_e32 v90, v0
	v_mov_b32_e32 v91, v0
	v_mov_b32_e32 v92, v0
	v_mov_b32_e32 v93, v0
	v_mov_b32_e32 v94, v0
	v_mov_b32_e32 v95, v0
	v_mov_b32_e32 v96, v0
	v_mov_b32_e32 v97, v0
	v_mov_b32_e32 v130, v0
	v_mov_b32_e32 v131, v0
	v_mov_b32_e32 v132, v0
	v_mov_b32_e32 v133, v0
	v_mov_b32_e32 v134, v0
	v_mov_b32_e32 v135, v0
	v_mov_b32_e32 v136, v0
	v_mov_b32_e32 v137, v0
	v_mov_b32_e32 v114, v0
	v_mov_b32_e32 v115, v0
	v_mov_b32_e32 v116, v0
	v_mov_b32_e32 v117, v0
	v_mov_b32_e32 v118, v0
	v_mov_b32_e32 v119, v0
	v_mov_b32_e32 v120, v0
	v_mov_b32_e32 v121, v0
	s_barrier
	s_add_i32 s24, s50, 1
	s_cmp_eq_u32 s24, 0x7fffffff
	s_mov_b64 s[22:23], 0
	s_cbranch_scc0 .LBB0_941

; #define PG8_STAGE(bufoff, gbase, voff) do { _Pragma("unroll") for (int _i = 0; _i < 2; ++_i) \
;         __builtin_amdgcn_global_load_lds((const unsigned*)((const char*)(gbase) + (voff)[_i]), (PG8_LAS unsigned*)(lds + (bufoff) + ldsw + _i * 8192), 16, 0, 0); } while (0)
; #define PG8_WAIT_V(n) asm volatile("s_waitcnt vmcnt(" #n ")" ::: "memory")
; #define PG8_BAR __builtin_amdgcn_s_barrier()
; template <class Epi, class Sched, bool ALIGN_EPI = false, bool SP2 = false, bool KHOOK = false>
; __device__ __forceinline__ void gemm_phase(PG8_LAS unsigned char* lds, const Gemm g, const Sched& S, const Epi& E, const int tid_in) {
;     ...
;     if constexpr (SP2) {
;         PG8_STAGE(PG8_SB(0, 0), cB, voffB); PG8_STAGE(PG8_SB(0, 1), cB + hstep, voffB); PG8_STAGE(PG8_SA(0, 0), cA, voffA); PG8_STAGE(PG8_SA(0, 1), cA + hstep, voffA);
;         if (wr == 1) PG8_BAR;
;         PG8_WAIT_V(2); PG8_BAR;
;         PG8_STAGE(PG8_SB(1, 0), cB + kstep, voffB); PG8_STAGE(PG8_SA(1, 0), cA + kstep, voffA); PG8_STAGE(PG8_SB(1, 1), cB + hstep + kstep, voffB);
;         PG8_WAIT_V(6); PG8_BAR;
.LBB0_1056:
	v_lshrrev_b32_e32 v16, 1, v6
	v_and_b32_e32 v16, 24, v16
	s_lshl_b32 s5, s5, 5
	v_and_b32_e32 v7, 15, v6
	v_lshlrev_b32_e32 v17, 1, v16
	v_lshlrev_b32_e32 v6, 2, v6
	s_and_b32 s12, s5, 0x60
	v_lshl_add_u64 v[8:9], s[30:31], 0, v[32:33]
	v_mov_b32_e32 v131, v33
	v_readlane_b32 s26, v254, 14
	v_lshl_or_b32 v136, s10, 6, v7
	v_lshl_or_b32 v7, v7, 6, v17
	s_lshl_b32 s10, s10, 13
	v_and_b32_e32 v6, 32, v6
	s_lshl_b32 s5, s12, 7
	v_lshl_add_u64 v[10:11], s[30:31], 0, v[130:131]
	v_readlane_b32 s27, v254, 15
	v_bitop3_b32 v17, v7, s10, v6 bitop3:0xde
	v_bitop3_b32 v137, s5, v7, v6 bitop3:0xf6
	s_add_i32 m0, s36, 0x18000
	v_lshl_add_u64 v[6:7], v[8:9], 0, s[90:91]
	v_lshl_add_u64 v[12:13], s[26:27], 0, v[32:33]
	global_load_lds_dwordx4 v[6:7], off
	v_lshl_add_u64 v[6:7], v[10:11], 0, s[90:91]
	s_add_i32 m0, s36, 0x1a000
	s_add_i32 s40, s36, 0x8000
	s_add_i32 s41, s36, 0xa000
	v_lshl_add_u64 v[14:15], s[26:27], 0, v[130:131]
	global_load_lds_dwordx4 v[6:7], off
	v_lshl_add_u64 v[6:7], v[12:13], 0, s[90:91]
	s_mov_b32 m0, s40
	s_add_u32 s10, s30, 0x80080
	global_load_lds_dwordx4 v[6:7], off
	v_lshl_add_u64 v[6:7], v[14:15], 0, s[90:91]
	s_mov_b32 m0, s41
	s_addc_u32 s11, s31, 0
	global_load_lds_dwordx4 v[6:7], off
	s_add_i32 m0, s36, 0x1c000
	v_lshl_add_u64 v[6:7], s[10:11], 0, v[32:33]
	global_load_lds_dwordx4 v[6:7], off
	v_lshl_add_u64 v[6:7], s[10:11], 0, v[130:131]
	s_add_i32 m0, s36, 0x1e000
	s_cmpk_lt_u32 s4, 0x100
	global_load_lds_dwordx4 v[6:7], off
	s_waitcnt vmcnt(2)
	s_barrier
	v_lshlrev_b32_e32 v6, 15, v3
	v_and_b32_e32 v6, 0xffff0000, v6
	v_lshl_add_u32 v4, v4, 12, v6
	v_and_b32_e32 v3, 1, v3
	v_lshl_or_b32 v3, v3, 6, v4
	v_lshl_add_u32 v132, v5, 1, v3
	v_lshlrev_b32_e32 v3, 15, v0
	v_and_b32_e32 v3, 0xffff0000, v3
	s_waitcnt vmcnt(6)
	v_lshl_add_u32 v1, v1, 12, v3
	v_and_b32_e32 v0, 1, v0
	v_lshl_or_b32 v0, v0, 6, v1
	v_readlane_b32 s10, v254, 8
	v_readlane_b32 s14, v254, 10
	s_cselect_b64 s[4:5], -1, 0
	v_or_b32_e32 v138, s12, v16
	v_mov_b32_e32 v133, v33
	v_lshl_add_u32 v134, v2, 1, v0
	v_mov_b32_e32 v135, v33
	s_mov_b32 s42, 0
	v_add_u32_e32 v139, 0, v17
	s_mov_b32 s18, s10
	s_mov_b32 s19, s14
	s_barrier
	v_readlane_b32 s11, v254, 9
	v_readlane_b32 s15, v254, 11
	s_branch .LBB0_1059

; #define GPROBE_BEGIN(id) do { if (((PROBE_GEMM_SEL >> (id)) & 1) && blockIdx.x == 0 && tid_in < 64 && g.N == 20480) { volatile PG8_LAS unsigned long long* PW_ = (volatile PG8_LAS unsigned long long*)(lds + 163840 - 512 + 64); PW_[0] = __builtin_amdgcn_s_memrealtime(); } } while (0)
; #define GPROBE_END(id) do { if (((PROBE_GEMM_SEL >> (id)) & 1) && blockIdx.x == 0 && tid_in < 64 && g.N == 20480) { volatile PG8_LAS unsigned long long* PW_ = (volatile PG8_LAS unsigned long long*)(lds + 163840 - 512 + 64); PW_[1] += __builtin_amdgcn_s_memrealtime() - PW_[0]; } } while (0)
; #define PG8_STAGE(bufoff, gbase, voff) do { _Pragma("unroll") for (int _i = 0; _i < 2; ++_i) \
;         __builtin_amdgcn_global_load_lds((const unsigned*)((const char*)(gbase) + (voff)[_i]), (PG8_LAS unsigned*)(lds + (bufoff) + ldsw + _i * 8192), 16, 0, 0); } while (0)
; #define PG8_BAR __builtin_amdgcn_s_barrier()
; template <class Epi, class Sched, bool ALIGN_EPI = false, bool SP2 = false, bool KHOOK = false>
; __device__ __forceinline__ void gemm_phase(PG8_LAS unsigned char* lds, const Gemm g, const Sched& S, const Epi& E, const int tid_in) {
;     ...
;         const char* nA = has_next ? (const char*)g.A + (size_t)nxt.pm * tstep + (size_t)nxt.pn * ksl : cA; const char* nB = has_next ? (const char*)g.Bt + (size_t)nxt.pn * bts + (size_t)nxt.pn * ksl + (gdv ? (size_t)(nxt.pm / gdv) * gst : 0) : cB;
;         GPROBE_END(2); GPROBE_BEGIN(1);
;         for (int t = 0; t < nt; t += 2) {
;             const bool last = (t == nt - 2);
;             const char* a1 = cA + (size_t)(t + 1) * kstep;
;             const char* a2 = last ? nA : cA + (size_t)(t + 2) * kstep; const char* b2 = last ? nB : cB + (size_t)(t + 2) * kstep;
;             const char* a3 = a2 + kstep; const char* b3 = b2 + kstep;
;             if (last && has_next) S.a_ready(nxt);
;             if constexpr (SP2) {
;             PG8_LDB(B0, 0, 0); PG8_LDB(B1, 0, 1); PG8_SCHED; PG8_LDA(At, 0, 0); PG8_STAGE(PG8_SA(1, 1), a1 + hstep, voffA);
;             PG8_WAIT_V(8); PG8_WAIT_L(0); PG8_BAR; PG8_MMA(0, 0, At, B0); PG8_MMA(0, 1, At, B1); PG8_BAR; PG8_SCHED;
;             PG8_LDA(At, 0, 1); PG8_STAGE(PG8_SB(0, 0), b2, voffB); PG8_STAGE(PG8_SB(0, 1), b2 + hstep, voffB); PG8_STAGE(PG8_SA(0, 0), a2, voffA);
;             PG8_WAIT_V(8); PG8_WAIT_L(0); PG8_BAR; PG8_MMA(1, 0, At, B0); PG8_MMA(1, 1, At, B1); PG8_BAR; PG8_SCHED;
.LBB0_1062:
	s_ashr_i32 s13, s12, 31
	s_lshl_b64 s[16:17], s[12:13], 20
	v_readlane_b32 s22, v254, 34
	v_readlane_b32 s23, v254, 35
	s_add_u32 s16, s22, s16
	s_addc_u32 s17, s23, s17
	s_and_b64 s[22:23], s[14:15], exec
	s_cselect_b32 s13, s17, s27
	s_cselect_b32 s24, s16, s26
	s_ashr_i32 s11, s10, 31
	s_lshl_b64 s[22:23], s[10:11], 20
	s_add_u32 s22, s2, s22
	s_addc_u32 s23, s20, s23
	s_and_b64 s[44:45], s[14:15], exec
	s_cselect_b32 s11, s23, s31
	s_cselect_b32 s25, s22, s30
	s_add_u32 s26, s26, 0x80080
	s_addc_u32 s27, s27, 0
	s_add_u32 s44, s30, 0x100
	s_addc_u32 s45, s31, 0
	s_mov_b32 s46, -2
	s_add_u32 s30, s26, 0xfff80080
	s_addc_u32 s31, s27, -1
	s_add_i32 s47, 0, 0x10000
	s_cmp_eq_u32 s46, 28
	s_cselect_b32 s49, s13, s31
	s_cselect_b32 s48, s24, s30
	s_cselect_b32 s31, s11, s45
	s_cselect_b32 s30, s25, s44
	s_add_i32 s52, 0, 0x14000
	v_add_u32_e32 v152, s47, v137
	v_add_u32_e32 v168, s52, v137
	ds_read_b128 v[140:143], v152
	ds_read_b128 v[144:147], v152 offset:1024
	ds_read_b128 v[148:151], v152 offset:2048
	ds_read_b128 v[152:155], v152 offset:3072
	ds_read_b128 v[156:159], v168
	ds_read_b128 v[160:163], v168 offset:1024
	ds_read_b128 v[164:167], v168 offset:2048
	ds_read_b128 v[168:171], v168 offset:3072
	v_lshl_add_u64 v[192:193], s[26:27], 0, v[132:133]
	s_add_i32 m0, s36, 0xc000
	ds_read_b128 v[172:175], v139
	ds_read_b128 v[176:179], v139 offset:1024
	ds_read_b128 v[180:183], v139 offset:2048
	ds_read_b128 v[184:187], v139 offset:3072
	ds_read_b128 v[188:191], v139 offset:4096
	ds_read_b128 v[198:201], v139 offset:5120
	ds_read_b128 v[202:205], v139 offset:6144
	ds_read_b128 v[206:209], v139 offset:7168
	global_load_lds_dwordx4 v[192:193], off
	v_lshl_add_u64 v[192:193], s[26:27], 0, v[134:135]
	s_add_i32 m0, s36, 0xe000
	s_nop 0
	global_load_lds_dwordx4 v[192:193], off
	s_waitcnt vmcnt(10)
	s_waitcnt lgkmcnt(0)
	s_barrier
	s_setprio 1
	s_waitcnt lgkmcnt(0)
	v_mfma_f32_16x16x32_bf16 v[126:129], v[140:143], v[172:175], 0
	v_mfma_f32_16x16x32_bf16 v[122:125], v[148:151], v[172:175], 0
	v_mfma_f32_16x16x32_bf16 v[110:113], v[140:143], v[180:183], 0
	v_mfma_f32_16x16x32_bf16 v[106:109], v[148:151], v[180:183], 0
	v_mfma_f32_16x16x32_bf16 v[94:97], v[140:143], v[188:191], 0
	v_mfma_f32_16x16x32_bf16 v[90:93], v[148:151], v[188:191], 0
	v_mfma_f32_16x16x32_bf16 v[78:81], v[140:143], v[202:205], 0
	v_mfma_f32_16x16x32_bf16 v[74:77], v[148:151], v[202:205], 0
	v_mfma_f32_16x16x32_bf16 v[126:129], v[144:147], v[176:179], v[126:129]
	v_mfma_f32_16x16x32_bf16 v[122:125], v[152:155], v[176:179], v[122:125]
	v_mfma_f32_16x16x32_bf16 v[110:113], v[144:147], v[184:187], v[110:113]
	v_mfma_f32_16x16x32_bf16 v[106:109], v[152:155], v[184:187], v[106:109]
	v_mfma_f32_16x16x32_bf16 v[94:97], v[144:147], v[198:201], v[94:97]
	v_mfma_f32_16x16x32_bf16 v[90:93], v[152:155], v[198:201], v[90:93]
	v_mfma_f32_16x16x32_bf16 v[78:81], v[144:147], v[206:209], v[78:81]
	v_mfma_f32_16x16x32_bf16 v[74:77], v[152:155], v[206:209], v[74:77]
	s_setprio 0
	s_setprio 1
	v_mfma_f32_16x16x32_bf16 v[118:121], v[156:159], v[172:175], 0
	v_mfma_f32_16x16x32_bf16 v[114:117], v[164:167], v[172:175], 0
	v_mfma_f32_16x16x32_bf16 v[102:105], v[156:159], v[180:183], 0
	v_mfma_f32_16x16x32_bf16 v[98:101], v[164:167], v[180:183], 0
	v_mfma_f32_16x16x32_bf16 v[86:89], v[156:159], v[188:191], 0
	v_mfma_f32_16x16x32_bf16 v[82:85], v[164:167], v[188:191], 0
	v_mfma_f32_16x16x32_bf16 v[70:73], v[156:159], v[202:205], 0
	v_mfma_f32_16x16x32_bf16 v[66:69], v[164:167], v[202:205], 0
	v_mfma_f32_16x16x32_bf16 v[118:121], v[160:163], v[176:179], v[118:121]
	v_mfma_f32_16x16x32_bf16 v[114:117], v[168:171], v[176:179], v[114:117]
	v_mfma_f32_16x16x32_bf16 v[102:105], v[160:163], v[184:187], v[102:105]
	v_mfma_f32_16x16x32_bf16 v[98:101], v[168:171], v[184:187], v[98:101]
	v_mfma_f32_16x16x32_bf16 v[86:89], v[160:163], v[198:201], v[86:89]
	v_mfma_f32_16x16x32_bf16 v[82:85], v[168:171], v[198:201], v[82:85]
	v_mfma_f32_16x16x32_bf16 v[70:73], v[160:163], v[206:209], v[70:73]
	v_mfma_f32_16x16x32_bf16 v[66:69], v[168:171], v[206:209], v[66:69]
	s_setprio 0
	s_barrier
	s_add_i32 s47, s47, s33
	v_lshl_add_u64 v[192:193], s[30:31], 0, v[32:33]
	s_mov_b32 m0, s47
	ds_read_b128 v[172:175], v139 offset:16384
	ds_read_b128 v[176:179], v139 offset:17408
	ds_read_b128 v[180:183], v139 offset:18432
	ds_read_b128 v[184:187], v139 offset:19456
	ds_read_b128 v[188:191], v139 offset:20480
	ds_read_b128 v[198:201], v139 offset:21504
	ds_read_b128 v[202:205], v139 offset:22528
	ds_read_b128 v[206:209], v139 offset:23552
	global_load_lds_dwordx4 v[192:193], off
	s_add_i32 m0, s47, 0x2000
	s_add_u32 s50, s30, 0x80000
	v_lshl_add_u64 v[210:211], s[30:31], 0, v[130:131]
	s_addc_u32 s51, s31, 0
	s_add_i32 s47, s52, s33
	global_load_lds_dwordx4 v[210:211], off
	v_lshl_add_u64 v[212:213], s[50:51], 0, v[32:33]
	s_mov_b32 m0, s47
	v_lshl_add_u64 v[214:215], s[48:49], 0, v[130:131]
	global_load_lds_dwordx4 v[212:213], off
	v_lshl_add_u64 v[212:213], s[50:51], 0, v[130:131]
	s_add_i32 m0, s47, 0x2000
	s_nop 0
	global_load_lds_dwordx4 v[212:213], off
	v_lshl_add_u64 v[212:213], s[48:49], 0, v[32:33]
	s_mov_b32 m0, s36
	s_nop 0
	global_load_lds_dwordx4 v[212:213], off
	s_mov_b32 m0, s37
	s_nop 0
	global_load_lds_dwordx4 v[214:215], off
	s_waitcnt vmcnt(16)
	s_waitcnt lgkmcnt(0)
	s_barrier
; #define PG8_STAGE(bufoff, gbase, voff) do { _Pragma("unroll") for (int _i = 0; _i < 2; ++_i) \
;         __builtin_amdgcn_global_load_lds((const unsigned*)((const char*)(gbase) + (voff)[_i]), (PG8_LAS unsigned*)(lds + (bufoff) + ldsw + _i * 8192), 16, 0, 0); } while (0)
; #define PG8_LDA(dst, b, h) do { _Pragma("unroll") for (int m = 0; m < 4; ++m) _Pragma("unroll") for (int k = 0; k < 2; ++k) dst[m][k] = *(const PG8_LAS bf16x8*)(lds + PG8_SA(b, h) + aoff + m * 2048 + k * 1024); } while (0)
; #define PG8_LDB(dst, b, h) do { _Pragma("unroll") for (int n = 0; n < 2; ++n) _Pragma("unroll") for (int k = 0; k < 2; ++k) dst[n][k] = *(const PG8_LAS bf16x8*)(lds + PG8_SB(b, h) + boff + n * 2048 + k * 1024); } while (0)
; #define PG8_MMA(ai, bj, At, Bt) do { __builtin_amdgcn_s_setprio(1); _Pragma("unroll") for (int m = 0; m < 4; ++m) _Pragma("unroll") for (int n = 0; n < 2; ++n) _Pragma("unroll") for (int k = 0; k < 2; ++k) \
;         acc[ai][bj][m][n] = __builtin_amdgcn_mfma_f32_16x16x32_bf16(Bt[n][k], At[m][k], acc[ai][bj][m][n], 0, 0, 0); __builtin_amdgcn_s_setprio(0); } while (0)
; #define PG8_WAIT_V(n) asm volatile("s_waitcnt vmcnt(" #n ")" ::: "memory")
; #define PG8_WAIT_L(n) asm volatile("s_waitcnt lgkmcnt(" #n ")" ::: "memory")
; #define PG8_BAR __builtin_amdgcn_s_barrier()
; #define PG8_SCHED __builtin_amdgcn_sched_barrier(0)
; template <class Epi, class Sched, bool ALIGN_EPI = false, bool SP2 = false, bool KHOOK = false>
; __device__ __forceinline__ void gemm_phase(PG8_LAS unsigned char* lds, const Gemm g, const Sched& S, const Epi& E, const int tid_in) {
;     ...
;             PG8_WAIT_V(8); PG8_WAIT_L(0); PG8_BAR; PG8_MMA(1, 0, At, B0); PG8_MMA(1, 1, At, B1); PG8_BAR; PG8_SCHED;
;             PG8_LDB(B0, 1, 0); PG8_LDB(B1, 1, 1); PG8_SCHED; PG8_LDA(At, 1, 0); PG8_STAGE(PG8_SA(0, 1), a2 + hstep, voffA);
;             PG8_WAIT_V(8); PG8_WAIT_L(0); PG8_BAR; PG8_MMA(0, 0, At, B0); PG8_MMA(0, 1, At, B1); PG8_BAR; PG8_SCHED;
	s_setprio 1
	s_waitcnt lgkmcnt(0)
	v_mfma_f32_16x16x32_bf16 v[62:65], v[140:143], v[172:175], 0
	v_mfma_f32_16x16x32_bf16 v[58:61], v[148:151], v[172:175], 0
	v_mfma_f32_16x16x32_bf16 v[46:49], v[140:143], v[180:183], 0
	v_mfma_f32_16x16x32_bf16 v[42:45], v[148:151], v[180:183], 0
	v_mfma_f32_16x16x32_bf16 v[28:31], v[140:143], v[188:191], 0
	v_mfma_f32_16x16x32_bf16 v[24:27], v[148:151], v[188:191], 0
	v_mfma_f32_16x16x32_bf16 v[12:15], v[140:143], v[202:205], 0
	v_mfma_f32_16x16x32_bf16 v[8:11], v[148:151], v[202:205], 0
	v_mfma_f32_16x16x32_bf16 v[62:65], v[144:147], v[176:179], v[62:65]
	v_mfma_f32_16x16x32_bf16 v[58:61], v[152:155], v[176:179], v[58:61]
	v_mfma_f32_16x16x32_bf16 v[46:49], v[144:147], v[184:187], v[46:49]
	v_mfma_f32_16x16x32_bf16 v[42:45], v[152:155], v[184:187], v[42:45]
	v_mfma_f32_16x16x32_bf16 v[28:31], v[144:147], v[198:201], v[28:31]
	v_mfma_f32_16x16x32_bf16 v[24:27], v[152:155], v[198:201], v[24:27]
	v_mfma_f32_16x16x32_bf16 v[12:15], v[144:147], v[206:209], v[12:15]
	v_mfma_f32_16x16x32_bf16 v[8:11], v[152:155], v[206:209], v[8:11]
	s_setprio 0
	s_setprio 1
	v_mfma_f32_16x16x32_bf16 v[54:57], v[156:159], v[172:175], 0
	v_mfma_f32_16x16x32_bf16 v[50:53], v[164:167], v[172:175], 0
	v_mfma_f32_16x16x32_bf16 v[38:41], v[156:159], v[180:183], 0
	v_mfma_f32_16x16x32_bf16 v[34:37], v[164:167], v[180:183], 0
	v_mfma_f32_16x16x32_bf16 v[20:23], v[156:159], v[188:191], 0
	v_mfma_f32_16x16x32_bf16 v[16:19], v[164:167], v[188:191], 0
	v_mfma_f32_16x16x32_bf16 v[4:7], v[156:159], v[202:205], 0
	v_mfma_f32_16x16x32_bf16 v[0:3], v[164:167], v[202:205], 0
	v_mfma_f32_16x16x32_bf16 v[54:57], v[160:163], v[176:179], v[54:57]
	v_mfma_f32_16x16x32_bf16 v[50:53], v[168:171], v[176:179], v[50:53]
	v_mfma_f32_16x16x32_bf16 v[38:41], v[160:163], v[184:187], v[38:41]
	v_mfma_f32_16x16x32_bf16 v[34:37], v[168:171], v[184:187], v[34:37]
	v_mfma_f32_16x16x32_bf16 v[20:23], v[160:163], v[198:201], v[20:23]
	v_mfma_f32_16x16x32_bf16 v[16:19], v[168:171], v[198:201], v[16:19]
	v_mfma_f32_16x16x32_bf16 v[4:7], v[160:163], v[206:209], v[4:7]
	v_mfma_f32_16x16x32_bf16 v[0:3], v[168:171], v[206:209], v[0:3]
	s_setprio 0
	s_barrier
	s_add_i32 s47, 0, 0x18000
	s_add_i32 s50, 0, 0x1c000
	v_add_u32_e32 v152, s47, v137
	v_add_u32_e32 v168, s50, v137
	ds_read_b128 v[140:143], v152
	ds_read_b128 v[144:147], v152 offset:1024
	ds_read_b128 v[148:151], v152 offset:2048
	ds_read_b128 v[152:155], v152 offset:3072
	ds_read_b128 v[156:159], v168
	ds_read_b128 v[160:163], v168 offset:1024
	ds_read_b128 v[164:167], v168 offset:2048
	ds_read_b128 v[168:171], v168 offset:3072
	s_add_u32 s48, s48, 0x80000
	s_addc_u32 s49, s49, 0
	s_mov_b32 m0, s38
	v_lshl_add_u64 v[216:217], s[48:49], 0, v[32:33]
	ds_read_b128 v[172:175], v139 offset:32768
	ds_read_b128 v[176:179], v139 offset:33792
	ds_read_b128 v[180:183], v139 offset:34816
	ds_read_b128 v[184:187], v139 offset:35840
	ds_read_b128 v[188:191], v139 offset:36864
	ds_read_b128 v[198:201], v139 offset:37888
	ds_read_b128 v[202:205], v139 offset:38912
	ds_read_b128 v[206:209], v139 offset:39936
	global_load_lds_dwordx4 v[216:217], off
	v_lshl_add_u64 v[216:217], s[48:49], 0, v[130:131]
	s_mov_b32 m0, s39
	s_nop 0
	global_load_lds_dwordx4 v[216:217], off
	s_waitcnt vmcnt(8)
	s_waitcnt lgkmcnt(0)
	s_barrier
	s_setprio 1
	s_waitcnt lgkmcnt(0)
	v_mfma_f32_16x16x32_bf16 v[126:129], v[140:143], v[172:175], v[126:129]
	v_mfma_f32_16x16x32_bf16 v[122:125], v[148:151], v[172:175], v[122:125]
	v_mfma_f32_16x16x32_bf16 v[110:113], v[140:143], v[180:183], v[110:113]
	v_mfma_f32_16x16x32_bf16 v[106:109], v[148:151], v[180:183], v[106:109]
	v_mfma_f32_16x16x32_bf16 v[94:97], v[140:143], v[188:191], v[94:97]
	v_mfma_f32_16x16x32_bf16 v[90:93], v[148:151], v[188:191], v[90:93]
	v_mfma_f32_16x16x32_bf16 v[78:81], v[140:143], v[202:205], v[78:81]
	v_mfma_f32_16x16x32_bf16 v[74:77], v[148:151], v[202:205], v[74:77]
	v_mfma_f32_16x16x32_bf16 v[126:129], v[144:147], v[176:179], v[126:129]
	v_mfma_f32_16x16x32_bf16 v[122:125], v[152:155], v[176:179], v[122:125]
	v_mfma_f32_16x16x32_bf16 v[110:113], v[144:147], v[184:187], v[110:113]
	v_mfma_f32_16x16x32_bf16 v[106:109], v[152:155], v[184:187], v[106:109]
	v_mfma_f32_16x16x32_bf16 v[94:97], v[144:147], v[198:201], v[94:97]
	v_mfma_f32_16x16x32_bf16 v[90:93], v[152:155], v[198:201], v[90:93]
	v_mfma_f32_16x16x32_bf16 v[78:81], v[144:147], v[206:209], v[78:81]
	v_mfma_f32_16x16x32_bf16 v[74:77], v[152:155], v[206:209], v[74:77]
	s_setprio 0
	s_setprio 1
	v_mfma_f32_16x16x32_bf16 v[118:121], v[156:159], v[172:175], v[118:121]
	v_mfma_f32_16x16x32_bf16 v[114:117], v[164:167], v[172:175], v[114:117]
	v_mfma_f32_16x16x32_bf16 v[102:105], v[156:159], v[180:183], v[102:105]
	v_mfma_f32_16x16x32_bf16 v[98:101], v[164:167], v[180:183], v[98:101]
	v_mfma_f32_16x16x32_bf16 v[86:89], v[156:159], v[188:191], v[86:89]
	v_mfma_f32_16x16x32_bf16 v[82:85], v[164:167], v[188:191], v[82:85]
	v_mfma_f32_16x16x32_bf16 v[70:73], v[156:159], v[202:205], v[70:73]
	v_mfma_f32_16x16x32_bf16 v[66:69], v[164:167], v[202:205], v[66:69]
	v_mfma_f32_16x16x32_bf16 v[118:121], v[160:163], v[176:179], v[118:121]
	v_mfma_f32_16x16x32_bf16 v[114:117], v[168:171], v[176:179], v[114:117]
	v_mfma_f32_16x16x32_bf16 v[102:105], v[160:163], v[184:187], v[102:105]
	v_mfma_f32_16x16x32_bf16 v[98:101], v[168:171], v[184:187], v[98:101]
	v_mfma_f32_16x16x32_bf16 v[86:89], v[160:163], v[198:201], v[86:89]
	v_mfma_f32_16x16x32_bf16 v[82:85], v[168:171], v[198:201], v[82:85]
	v_mfma_f32_16x16x32_bf16 v[70:73], v[160:163], v[206:209], v[70:73]
	v_mfma_f32_16x16x32_bf16 v[66:69], v[168:171], v[206:209], v[66:69]
	s_setprio 0
	s_barrier
; #define PG8_STAGE(bufoff, gbase, voff) do { _Pragma("unroll") for (int _i = 0; _i < 2; ++_i) \
;         __builtin_amdgcn_global_load_lds((const unsigned*)((const char*)(gbase) + (voff)[_i]), (PG8_LAS unsigned*)(lds + (bufoff) + ldsw + _i * 8192), 16, 0, 0); } while (0)
; #define PG8_LDA(dst, b, h) do { _Pragma("unroll") for (int m = 0; m < 4; ++m) _Pragma("unroll") for (int k = 0; k < 2; ++k) dst[m][k] = *(const PG8_LAS bf16x8*)(lds + PG8_SA(b, h) + aoff + m * 2048 + k * 1024); } while (0)
; #define PG8_MMA(ai, bj, At, Bt) do { __builtin_amdgcn_s_setprio(1); _Pragma("unroll") for (int m = 0; m < 4; ++m) _Pragma("unroll") for (int n = 0; n < 2; ++n) _Pragma("unroll") for (int k = 0; k < 2; ++k) \
;         acc[ai][bj][m][n] = __builtin_amdgcn_mfma_f32_16x16x32_bf16(Bt[n][k], At[m][k], acc[ai][bj][m][n], 0, 0, 0); __builtin_amdgcn_s_setprio(0); } while (0)
; #define PG8_WAIT_V(n) asm volatile("s_waitcnt vmcnt(" #n ")" ::: "memory")
; #define PG8_WAIT_L(n) asm volatile("s_waitcnt lgkmcnt(" #n ")" ::: "memory")
; #define PG8_BAR __builtin_amdgcn_s_barrier()
; #define PG8_SCHED __builtin_amdgcn_sched_barrier(0)
; template <class Epi, class Sched, bool ALIGN_EPI = false, bool SP2 = false, bool KHOOK = false>
; __device__ __forceinline__ void gemm_phase(PG8_LAS unsigned char* lds, const Gemm g, const Sched& S, const Epi& E, const int tid_in) {
;     ...
;         for (int t = 0; t < nt; t += 2) {
;             const bool last = (t == nt - 2);
;             const char* a1 = cA + (size_t)(t + 1) * kstep;
;             const char* a2 = last ? nA : cA + (size_t)(t + 2) * kstep; const char* b2 = last ? nB : cB + (size_t)(t + 2) * kstep;
;     ...
;             PG8_LDA(At, 1, 1); PG8_STAGE(PG8_SB(1, 0), b3, voffB); PG8_STAGE(PG8_SB(1, 1), b3 + hstep, voffB); PG8_STAGE(PG8_SA(1, 0), a3, voffA);
;             PG8_WAIT_V(8); PG8_WAIT_L(0); PG8_BAR; PG8_MMA(1, 0, At, B0); PG8_MMA(1, 1, At, B1); PG8_BAR; PG8_SCHED;
	s_add_i32 s47, s47, s33
	v_lshl_add_u64 v[192:193], v[192:193], 0, s[90:91]
	s_mov_b32 m0, s47
	ds_read_b128 v[172:175], v139 offset:49152
	ds_read_b128 v[176:179], v139 offset:50176
	ds_read_b128 v[180:183], v139 offset:51200
	ds_read_b128 v[184:187], v139 offset:52224
	ds_read_b128 v[188:191], v139 offset:53248
	ds_read_b128 v[198:201], v139 offset:54272
	ds_read_b128 v[202:205], v139 offset:55296
	ds_read_b128 v[206:209], v139 offset:56320
	global_load_lds_dwordx4 v[192:193], off
	s_add_i32 m0, s47, 0x2000
	s_add_u32 s30, s30, 0x80080
	v_lshl_add_u64 v[192:193], v[210:211], 0, s[90:91]
	s_addc_u32 s31, s31, 0
	s_add_i32 s47, s50, s33
	global_load_lds_dwordx4 v[192:193], off
	v_lshl_add_u64 v[192:193], s[30:31], 0, v[32:33]
	s_mov_b32 m0, s47
	s_nop 0
	global_load_lds_dwordx4 v[192:193], off
	v_lshl_add_u64 v[192:193], s[30:31], 0, v[130:131]
	s_add_i32 m0, s47, 0x2000
	s_nop 0
	global_load_lds_dwordx4 v[192:193], off
	v_lshl_add_u64 v[192:193], v[212:213], 0, s[90:91]
	s_mov_b32 m0, s40
	s_nop 0
	global_load_lds_dwordx4 v[192:193], off
	v_lshl_add_u64 v[192:193], v[214:215], 0, s[90:91]
	s_mov_b32 m0, s41
	s_nop 0
	global_load_lds_dwordx4 v[192:193], off
	s_waitcnt vmcnt(8)
	s_waitcnt lgkmcnt(0)
	s_barrier
	s_setprio 1
	s_waitcnt lgkmcnt(0)
	v_mfma_f32_16x16x32_bf16 v[62:65], v[140:143], v[172:175], v[62:65]
	v_mfma_f32_16x16x32_bf16 v[58:61], v[148:151], v[172:175], v[58:61]
	v_mfma_f32_16x16x32_bf16 v[46:49], v[140:143], v[180:183], v[46:49]
	v_mfma_f32_16x16x32_bf16 v[42:45], v[148:151], v[180:183], v[42:45]
	v_mfma_f32_16x16x32_bf16 v[28:31], v[140:143], v[188:191], v[28:31]
	v_mfma_f32_16x16x32_bf16 v[24:27], v[148:151], v[188:191], v[24:27]
	v_mfma_f32_16x16x32_bf16 v[12:15], v[140:143], v[202:205], v[12:15]
	v_mfma_f32_16x16x32_bf16 v[8:11], v[148:151], v[202:205], v[8:11]
	v_mfma_f32_16x16x32_bf16 v[62:65], v[144:147], v[176:179], v[62:65]
	v_mfma_f32_16x16x32_bf16 v[58:61], v[152:155], v[176:179], v[58:61]
	v_mfma_f32_16x16x32_bf16 v[46:49], v[144:147], v[184:187], v[46:49]
	v_mfma_f32_16x16x32_bf16 v[42:45], v[152:155], v[184:187], v[42:45]
	v_mfma_f32_16x16x32_bf16 v[28:31], v[144:147], v[198:201], v[28:31]
	v_mfma_f32_16x16x32_bf16 v[24:27], v[152:155], v[198:201], v[24:27]
	v_mfma_f32_16x16x32_bf16 v[12:15], v[144:147], v[206:209], v[12:15]
	v_mfma_f32_16x16x32_bf16 v[8:11], v[152:155], v[206:209], v[8:11]
	s_setprio 0
	s_setprio 1
	v_mfma_f32_16x16x32_bf16 v[54:57], v[156:159], v[172:175], v[54:57]
	v_mfma_f32_16x16x32_bf16 v[50:53], v[164:167], v[172:175], v[50:53]
	v_mfma_f32_16x16x32_bf16 v[38:41], v[156:159], v[180:183], v[38:41]
	v_mfma_f32_16x16x32_bf16 v[34:37], v[164:167], v[180:183], v[34:37]
	v_mfma_f32_16x16x32_bf16 v[20:23], v[156:159], v[188:191], v[20:23]
	v_mfma_f32_16x16x32_bf16 v[16:19], v[164:167], v[188:191], v[16:19]
	v_mfma_f32_16x16x32_bf16 v[4:7], v[156:159], v[202:205], v[4:7]
	v_mfma_f32_16x16x32_bf16 v[0:3], v[164:167], v[202:205], v[0:3]
	v_mfma_f32_16x16x32_bf16 v[54:57], v[160:163], v[176:179], v[54:57]
	v_mfma_f32_16x16x32_bf16 v[50:53], v[168:171], v[176:179], v[50:53]
	v_mfma_f32_16x16x32_bf16 v[38:41], v[160:163], v[184:187], v[38:41]
	v_mfma_f32_16x16x32_bf16 v[34:37], v[168:171], v[184:187], v[34:37]
	v_mfma_f32_16x16x32_bf16 v[20:23], v[160:163], v[198:201], v[20:23]
	v_mfma_f32_16x16x32_bf16 v[16:19], v[168:171], v[198:201], v[16:19]
	v_mfma_f32_16x16x32_bf16 v[4:7], v[160:163], v[206:209], v[4:7]
	v_mfma_f32_16x16x32_bf16 v[0:3], v[168:171], v[206:209], v[0:3]
	s_setprio 0
	s_barrier
	s_add_i32 s46, s46, 2
	s_add_u32 s26, s26, 0x100
	s_addc_u32 s27, s27, 0
	s_add_u32 s44, s44, 0x100
	s_addc_u32 s45, s45, 0
	s_cmp_gt_u32 s46, 29

; #define PG8_STAGE(bufoff, gbase, voff) do { _Pragma("unroll") for (int _i = 0; _i < 2; ++_i) \
;         __builtin_amdgcn_global_load_lds((const unsigned*)((const char*)(gbase) + (voff)[_i]), (PG8_LAS unsigned*)(lds + (bufoff) + ldsw + _i * 8192), 16, 0, 0); } while (0)
; #define PG8_WAIT_V(n) asm volatile("s_waitcnt vmcnt(" #n ")" ::: "memory")
; #define PG8_BAR __builtin_amdgcn_s_barrier()
; template <class Epi, class Sched, bool ALIGN_EPI = false, bool SP2 = false, bool KHOOK = false>
; __device__ __forceinline__ void gemm_phase(PG8_LAS unsigned char* lds, const Gemm g, const Sched& S, const Epi& E, const int tid_in) {
;     ...
;     if constexpr (SP2) {
;         PG8_STAGE(PG8_SB(0, 0), cB, voffB); PG8_STAGE(PG8_SB(0, 1), cB + hstep, voffB); PG8_STAGE(PG8_SA(0, 0), cA, voffA); PG8_STAGE(PG8_SA(0, 1), cA + hstep, voffA);
;         if (wr == 1) PG8_BAR;
;         PG8_WAIT_V(2); PG8_BAR;
;         PG8_STAGE(PG8_SB(1, 0), cB + kstep, voffB); PG8_STAGE(PG8_SA(1, 0), cA + kstep, voffA); PG8_STAGE(PG8_SB(1, 1), cB + hstep + kstep, voffB);
;         PG8_WAIT_V(6); PG8_BAR;
.LBB0_1074:
	s_lshl_b64 s[4:5], s[96:97], 25
	v_readlane_b32 s17, v252, 59
	s_add_u32 s4, s17, s4
	v_readlane_b32 s17, v252, 60
	v_lshrrev_b32_e32 v10, 1, v8
	s_addc_u32 s5, s17, s5
	v_and_b32_e32 v10, 24, v10
	s_lshl_b32 s11, s11, 5
	v_and_b32_e32 v9, 15, v8
	v_lshlrev_b32_e32 v11, 1, v10
	v_lshlrev_b32_e32 v8, 2, v8
	s_and_b32 s18, s11, 0x60
	s_add_i32 m0, s38, 0x18000
	v_lshl_add_u64 v[6:7], v[6:7], 0, s[90:91]
	v_lshl_or_b32 v136, s16, 6, v9
	v_lshl_or_b32 v9, v9, 6, v11
	s_lshl_b32 s16, s16, 13
	v_and_b32_e32 v8, 32, v8
	s_lshl_b32 s11, s18, 7
	global_load_lds_dwordx4 v[6:7], off
	v_lshl_add_u64 v[4:5], v[4:5], 0, s[90:91]
	s_add_i32 m0, s38, 0x1a000
	s_add_i32 s24, s38, 0x8000
	s_add_i32 s25, s38, 0xa000
	v_bitop3_b32 v11, v9, s16, v8 bitop3:0xde
	global_load_lds_dwordx4 v[4:5], off
	v_lshl_add_u64 v[0:1], v[0:1], 0, s[90:91]
	s_mov_b32 m0, s24
	s_add_u32 s16, s12, 0x10080
	global_load_lds_dwordx4 v[0:1], off
	v_lshl_add_u64 v[0:1], v[2:3], 0, s[90:91]
	s_mov_b32 m0, s25
	s_addc_u32 s17, s13, 0
	global_load_lds_dwordx4 v[0:1], off
	s_add_i32 m0, s38, 0x1c000
	v_lshl_add_u64 v[0:1], s[16:17], 0, v[32:33]
	global_load_lds_dwordx4 v[0:1], off
	v_lshl_add_u64 v[0:1], s[16:17], 0, v[130:131]
	s_add_i32 m0, s38, 0x1e000
	s_cmpk_lt_u32 s10, 0x100
	global_load_lds_dwordx4 v[0:1], off
	s_waitcnt vmcnt(2)
	s_barrier
	s_waitcnt vmcnt(6)
	v_or_b32_e32 v138, s18, v10
	v_readlane_b32 s16, v254, 20
	v_readlane_b32 s18, v254, 24
	v_bitop3_b32 v137, s11, v9, v8 bitop3:0xf6
	s_cselect_b64 s[10:11], -1, 0
	s_mov_b32 s42, 0
	v_add_u32_e32 v139, 0, v11
	s_mov_b32 s44, s16
	s_mov_b32 s45, s18
	s_barrier
	v_readlane_b32 s17, v254, 21
	v_readlane_b32 s19, v254, 25
	s_branch .LBB0_1077

; #define PG8_BAR __builtin_amdgcn_s_barrier()
; template <class Epi, class Sched, bool ALIGN_EPI = false, bool SP2 = false, bool KHOOK = false>
; __device__ __forceinline__ void gemm_phase(PG8_LAS unsigned char* lds, const Gemm g, const Sched& S, const Epi& E, const int tid_in) {
;     ...
;     for (int i = 0; i < 2; ++i) { int R, C; stage_rc(tid * 16 + i * 8192, R, C); const int Rb = Epi::PERM ? ((R & ~31) + perm32(R & 31)) : R;
;         voffA[i] = (unsigned)(R * LD + C) * 2u; voffB[i] = (unsigned)(Rb * LD + C) * 2u; }
;     const size_t kstep = (size_t)(BK * 2);
;     const size_t hstep = (size_t)HALF * LD * 2;
;     const size_t tstep = 2 * hstep;
;     const unsigned ldsw = (unsigned)wid * 1024u;
;     const int aoff = lds_byte(wr * 64 + fr, fq * 8), boff = lds_byte(wc * 32 + fr, fq * 8);
;     ...
;     Unit cur, nxt; int ui = 0;
;     if (!S.next(0, cur)) return;
;     f32x4 acc[2][2][4][2];
; #pragma unroll
;     for (int a = 0; a < 2; ++a)
; #pragma unroll
;         for (int b = 0; b < 2; ++b)
; #pragma unroll
;             for (int m = 0; m < 4; ++m)
; #pragma unroll
;                 for (int n = 0; n < 2; ++n) acc[a][b][m][n] = (f32x4){0.f, 0.f, 0.f, 0.f};
;     bf16x8 At[4][2], B0[2][2], B1[2][2];
;     const size_t ksl = g.splitk ? (size_t)K * 2 : 0, bts = g.splitk ? 0 : tstep;
;     const int gdv = g.gdiv; const size_t gst = g.gstride;
;     const char* cA = (const char*)g.A + (size_t)cur.pm * tstep + (size_t)cur.pn * ksl; const char* cB = (const char*)g.Bt + (size_t)cur.pn * bts + (size_t)cur.pn * ksl + (gdv ? (size_t)(cur.pm / gdv) * gst : 0);
;     S.a_ready(cur);
;     auto load_rr = [&](const Unit& uu) { if constexpr (KHOOK) { const int row = tid >> 1, hf = tid & 1; const f32x4 v = *(const f32x4*)(g.rr + ((size_t)(uu.pm * BM + row)) * 8 + 4 * hf);
;         PG8_LAS float* T = (PG8_LAS float*)(lds + 8 * 16384) + (4 * hf) * 256 + row; T[0] = v[0]; T[256] = v[1]; T[512] = v[2]; T[768] = v[3]; } };
;     load_rr(cur);
;     if constexpr (SP2) {
;         PG8_STAGE(PG8_SB(0, 0), cB, voffB); PG8_STAGE(PG8_SB(0, 1), cB + hstep, voffB); PG8_STAGE(PG8_SA(0, 0), cA, voffA); PG8_STAGE(PG8_SA(0, 1), cA + hstep, voffA);
;         if (wr == 1) PG8_BAR;
;         PG8_WAIT_V(2); PG8_BAR;
;         PG8_STAGE(PG8_SB(1, 0), cB + kstep, voffB); PG8_STAGE(PG8_SA(1, 0), cA + kstep, voffA); PG8_STAGE(PG8_SB(1, 1), cB + hstep + kstep, voffB);
;         PG8_WAIT_V(6); PG8_BAR;
.LBB0_1158:
	v_lshl_add_u64 v[8:9], s[22:23], 0, v[32:33]
	v_mov_b32_e32 v123, v33
	v_readlane_b32 s10, v254, 30
	v_and_b32_e32 v174, 15, v173
	v_and_b32_e32 v16, 48, v173
	v_lshlrev_b32_e32 v17, 2, v173
	v_lshl_add_u64 v[10:11], s[22:23], 0, v[122:123]
	v_mov_b32_e32 v127, v33
	v_readlane_b32 s11, v254, 31
	s_and_b32 s36, s1, 3
	s_lshl_b32 s0, s20, 13
	v_lshl_or_b32 v16, v174, 6, v16
	v_and_b32_e32 v17, 32, v17
	s_add_i32 m0, s40, 0x18000
	v_lshl_add_u64 v[8:9], v[8:9], 0, s[90:91]
	v_lshl_add_u64 v[12:13], s[10:11], 0, v[126:127]
	v_mov_b32_e32 v125, v33
	s_lshl_b32 s45, s20, 6
	v_bitop3_b32 v18, v16, s0, v17 bitop3:0xde
	s_lshl_b32 s0, s36, 12
	global_load_lds_dwordx4 v[8:9], off
	v_lshl_add_u64 v[8:9], v[10:11], 0, s[90:91]
	s_add_i32 m0, s40, 0x1a000
	s_add_i32 s46, s40, 0x8000
	s_add_i32 s47, s40, 0xa000
	v_lshl_add_u64 v[14:15], s[10:11], 0, v[124:125]
	global_load_lds_dwordx4 v[8:9], off
	v_lshl_add_u64 v[8:9], v[12:13], 0, s[90:91]
	s_mov_b32 m0, s46
	s_add_u32 s4, s22, 0x160080
	global_load_lds_dwordx4 v[8:9], off
	v_lshl_add_u64 v[8:9], v[14:15], 0, s[90:91]
	s_mov_b32 m0, s47
	s_addc_u32 s5, s23, 0
	global_load_lds_dwordx4 v[8:9], off
	s_add_i32 m0, s40, 0x1c000
	v_lshl_add_u64 v[8:9], s[4:5], 0, v[32:33]
	global_load_lds_dwordx4 v[8:9], off
	v_lshl_add_u64 v[8:9], s[4:5], 0, v[122:123]
	s_add_i32 m0, s40, 0x1e000
	s_movk_i32 s12, 0x1600
	global_load_lds_dwordx4 v[8:9], off
	s_waitcnt vmcnt(2)
	s_barrier
	v_bitop3_b32 v144, s0, v16, v17 bitop3:0xf6
	v_lshrrev_b32_e32 v5, 1, v5
	v_mul_lo_u32 v4, v4, s12
	s_mov_b32 s0, 0x16000
	v_mad_u64_u32 v[4:5], s[4:5], v5, s0, v[4:5]
	v_or_b32_e32 v4, v4, v6
	v_add_lshl_u32 v128, v4, v7, 1
	v_lshrrev_b32_e32 v4, 1, v0
	v_mul_lo_u32 v0, v1, s12
	v_mad_u64_u32 v[0:1], s[4:5], v4, s0, v[0:1]
	v_readlane_b32 s4, v254, 18
	s_waitcnt vmcnt(6)
	v_or_b32_e32 v0, v0, v2
	v_readlane_b32 s5, v254, 19
	v_add_lshl_u32 v138, v0, v3, 1
	v_mov_b32_e32 v0, 0
	s_mov_b32 s33, s4
	v_readlane_b32 s4, v253, 57
	v_or_b32_e32 v172, s45, v174
	v_mov_b32_e32 v129, v33
	v_mov_b32_e32 v139, v33
	s_mov_b32 s48, 0
	v_add_u32_e32 v145, 0, v18
	s_mov_b32 s0, s4
	v_mov_b32_e32 v1, v0
	v_mov_b32_e32 v2, v0
	v_mov_b32_e32 v3, v0
	v_mov_b32_e32 v4, v0
	v_mov_b32_e32 v5, v0
	v_mov_b32_e32 v6, v0
	v_mov_b32_e32 v7, v0
	v_mov_b32_e32 v16, v0
	v_mov_b32_e32 v17, v0
	v_mov_b32_e32 v18, v0
	v_mov_b32_e32 v19, v0
	v_mov_b32_e32 v20, v0
	v_mov_b32_e32 v21, v0
	v_mov_b32_e32 v22, v0
	v_mov_b32_e32 v23, v0
	v_mov_b32_e32 v34, v0
	v_mov_b32_e32 v35, v0
	v_mov_b32_e32 v36, v0
	v_mov_b32_e32 v37, v0
	v_mov_b32_e32 v38, v0
	v_mov_b32_e32 v39, v0
	v_mov_b32_e32 v40, v0
	v_mov_b32_e32 v41, v0
	v_mov_b32_e32 v50, v0
	v_mov_b32_e32 v51, v0
	v_mov_b32_e32 v52, v0
	v_mov_b32_e32 v53, v0
	v_mov_b32_e32 v54, v0
	v_mov_b32_e32 v55, v0
	v_mov_b32_e32 v56, v0
	v_mov_b32_e32 v57, v0
	v_mov_b32_e32 v8, v0
	v_mov_b32_e32 v9, v0
	v_mov_b32_e32 v10, v0
	v_mov_b32_e32 v11, v0
	v_mov_b32_e32 v12, v0
	v_mov_b32_e32 v13, v0
	v_mov_b32_e32 v14, v0
	v_mov_b32_e32 v15, v0
	v_mov_b32_e32 v24, v0
	v_mov_b32_e32 v25, v0
	v_mov_b32_e32 v26, v0
	v_mov_b32_e32 v27, v0
	v_mov_b32_e32 v28, v0
	v_mov_b32_e32 v29, v0
	v_mov_b32_e32 v30, v0
	v_mov_b32_e32 v31, v0
	v_mov_b32_e32 v42, v0
	v_mov_b32_e32 v43, v0
	v_mov_b32_e32 v44, v0
	v_mov_b32_e32 v45, v0
	v_mov_b32_e32 v46, v0
	v_mov_b32_e32 v47, v0
	v_mov_b32_e32 v48, v0
	v_mov_b32_e32 v49, v0
	v_mov_b32_e32 v58, v0
	v_mov_b32_e32 v59, v0
	v_mov_b32_e32 v60, v0
	v_mov_b32_e32 v61, v0
	v_mov_b32_e32 v62, v0
	v_mov_b32_e32 v63, v0
	v_mov_b32_e32 v64, v0
	v_mov_b32_e32 v65, v0
	v_mov_b32_e32 v66, v0
	v_mov_b32_e32 v67, v0
	v_mov_b32_e32 v68, v0
	v_mov_b32_e32 v69, v0
	v_mov_b32_e32 v70, v0
	v_mov_b32_e32 v71, v0
	v_mov_b32_e32 v72, v0
	v_mov_b32_e32 v73, v0
	v_mov_b32_e32 v82, v0
	v_mov_b32_e32 v83, v0
	v_mov_b32_e32 v84, v0
	v_mov_b32_e32 v85, v0
	v_mov_b32_e32 v86, v0
	v_mov_b32_e32 v87, v0
	v_mov_b32_e32 v88, v0
	v_mov_b32_e32 v89, v0
	v_mov_b32_e32 v106, v0
	v_mov_b32_e32 v107, v0
	v_mov_b32_e32 v108, v0
	v_mov_b32_e32 v109, v0
	v_mov_b32_e32 v110, v0
	v_mov_b32_e32 v111, v0
	v_mov_b32_e32 v112, v0
	v_mov_b32_e32 v113, v0
	v_mov_b32_e32 v98, v0
	v_mov_b32_e32 v99, v0
	v_mov_b32_e32 v100, v0
	v_mov_b32_e32 v101, v0
	v_mov_b32_e32 v102, v0
	v_mov_b32_e32 v103, v0
	v_mov_b32_e32 v104, v0
	v_mov_b32_e32 v105, v0
	v_mov_b32_e32 v74, v0
	v_mov_b32_e32 v75, v0
	v_mov_b32_e32 v76, v0
	v_mov_b32_e32 v77, v0
	v_mov_b32_e32 v78, v0
	v_mov_b32_e32 v79, v0
	v_mov_b32_e32 v80, v0
	v_mov_b32_e32 v81, v0
	v_mov_b32_e32 v90, v0
	v_mov_b32_e32 v91, v0
	v_mov_b32_e32 v92, v0
	v_mov_b32_e32 v93, v0
	v_mov_b32_e32 v94, v0
	v_mov_b32_e32 v95, v0
	v_mov_b32_e32 v96, v0
	v_mov_b32_e32 v97, v0
	v_mov_b32_e32 v130, v0
	v_mov_b32_e32 v131, v0
	v_mov_b32_e32 v132, v0
	v_mov_b32_e32 v133, v0
	v_mov_b32_e32 v134, v0
	v_mov_b32_e32 v135, v0
	v_mov_b32_e32 v136, v0
	v_mov_b32_e32 v137, v0
	v_mov_b32_e32 v114, v0
	v_mov_b32_e32 v115, v0
	v_mov_b32_e32 v116, v0
	v_mov_b32_e32 v117, v0
	v_mov_b32_e32 v118, v0
	v_mov_b32_e32 v119, v0
	v_mov_b32_e32 v120, v0
	v_mov_b32_e32 v121, v0
	s_barrier
	v_readlane_b32 s5, v253, 58
	s_add_i32 s24, s48, 1
	s_cmp_eq_u32 s24, 0x7fffffff
	s_mov_b64 s[14:15], 0
	s_cbranch_scc1 .LBB0_1165

; #define PG8_BAR __builtin_amdgcn_s_barrier()
; template <class Epi, class Sched, bool ALIGN_EPI = false, bool SP2 = false, bool KHOOK = false>
; __device__ __forceinline__ void gemm_phase(PG8_LAS unsigned char* lds, const Gemm g, const Sched& S, const Epi& E, const int tid_in) {
;     ...
;     for (int i = 0; i < 2; ++i) { int R, C; stage_rc(tid * 16 + i * 8192, R, C); const int Rb = Epi::PERM ? ((R & ~31) + perm32(R & 31)) : R;
;         voffA[i] = (unsigned)(R * LD + C) * 2u; voffB[i] = (unsigned)(Rb * LD + C) * 2u; }
;     const size_t kstep = (size_t)(BK * 2);
;     const size_t hstep = (size_t)HALF * LD * 2;
;     const size_t tstep = 2 * hstep;
;     const unsigned ldsw = (unsigned)wid * 1024u;
;     const int aoff = lds_byte(wr * 64 + fr, fq * 8), boff = lds_byte(wc * 32 + fr, fq * 8);
;     ...
;     Unit cur, nxt; int ui = 0;
;     if (!S.next(0, cur)) return;
;     f32x4 acc[2][2][4][2];
; #pragma unroll
;     for (int a = 0; a < 2; ++a)
; #pragma unroll
;         for (int b = 0; b < 2; ++b)
; #pragma unroll
;             for (int m = 0; m < 4; ++m)
; #pragma unroll
;                 for (int n = 0; n < 2; ++n) acc[a][b][m][n] = (f32x4){0.f, 0.f, 0.f, 0.f};
;     bf16x8 At[4][2], B0[2][2], B1[2][2];
;     const size_t ksl = g.splitk ? (size_t)K * 2 : 0, bts = g.splitk ? 0 : tstep;
;     const int gdv = g.gdiv; const size_t gst = g.gstride;
;     const char* cA = (const char*)g.A + (size_t)cur.pm * tstep + (size_t)cur.pn * ksl; const char* cB = (const char*)g.Bt + (size_t)cur.pn * bts + (size_t)cur.pn * ksl + (gdv ? (size_t)(cur.pm / gdv) * gst : 0);
;     S.a_ready(cur);
;     auto load_rr = [&](const Unit& uu) { if constexpr (KHOOK) { const int row = tid >> 1, hf = tid & 1; const f32x4 v = *(const f32x4*)(g.rr + ((size_t)(uu.pm * BM + row)) * 8 + 4 * hf);
;         PG8_LAS float* T = (PG8_LAS float*)(lds + 8 * 16384) + (4 * hf) * 256 + row; T[0] = v[0]; T[256] = v[1]; T[512] = v[2]; T[768] = v[3]; } };
;     load_rr(cur);
;     if constexpr (SP2) {
;         PG8_STAGE(PG8_SB(0, 0), cB, voffB); PG8_STAGE(PG8_SB(0, 1), cB + hstep, voffB); PG8_STAGE(PG8_SA(0, 0), cA, voffA); PG8_STAGE(PG8_SA(0, 1), cA + hstep, voffA);
;         if (wr == 1) PG8_BAR;
;         PG8_WAIT_V(2); PG8_BAR;
;         PG8_STAGE(PG8_SB(1, 0), cB + kstep, voffB); PG8_STAGE(PG8_SA(1, 0), cA + kstep, voffA); PG8_STAGE(PG8_SB(1, 1), cB + hstep + kstep, voffB);
;         PG8_WAIT_V(6); PG8_BAR;
.LBB0_1278:
	v_lshl_add_u64 v[6:7], s[30:31], 0, v[32:33]
	v_mov_b32_e32 v131, v33
	v_readlane_b32 s12, v254, 36
	v_and_b32_e32 v216, 15, v215
	v_and_b32_e32 v14, 48, v215
	v_lshlrev_b32_e32 v15, 2, v215
	v_lshl_add_u64 v[8:9], s[30:31], 0, v[130:131]
	v_mov_b32_e32 v135, v33
	v_readlane_b32 s13, v254, 37
	s_and_b32 s2, s1, 3
	s_lshl_b32 s0, s19, 13
	v_lshl_or_b32 v14, v216, 6, v14
	v_and_b32_e32 v15, 32, v15
	s_add_i32 m0, s38, 0x18000
	v_lshl_add_u64 v[6:7], v[6:7], 0, s[90:91]
	v_lshl_add_u64 v[10:11], s[12:13], 0, v[134:135]
	v_mov_b32_e32 v133, v33
	s_lshl_b32 s41, s19, 6
	v_bitop3_b32 v16, v14, s0, v15 bitop3:0xde
	s_lshl_b32 s0, s2, 12
	global_load_lds_dwordx4 v[6:7], off
	v_lshl_add_u64 v[6:7], v[8:9], 0, s[90:91]
	s_add_i32 m0, s38, 0x1a000
	s_add_i32 s44, s38, 0x8000
	s_add_i32 s45, s38, 0xa000
	v_lshl_add_u64 v[12:13], s[12:13], 0, v[132:133]
	global_load_lds_dwordx4 v[6:7], off
	v_lshl_add_u64 v[6:7], v[10:11], 0, s[90:91]
	s_mov_b32 m0, s44
	s_add_u32 s4, s30, 0x80080
	global_load_lds_dwordx4 v[6:7], off
	v_lshl_add_u64 v[6:7], v[12:13], 0, s[90:91]
	s_mov_b32 m0, s45
	s_addc_u32 s5, s31, 0
	global_load_lds_dwordx4 v[6:7], off
	s_add_i32 m0, s38, 0x1c000
	v_lshl_add_u64 v[6:7], s[4:5], 0, v[32:33]
	global_load_lds_dwordx4 v[6:7], off
	v_lshl_add_u64 v[6:7], s[4:5], 0, v[130:131]
	s_add_i32 m0, s38, 0x1e000
	v_readlane_b32 s4, v254, 18
	global_load_lds_dwordx4 v[6:7], off
	s_waitcnt vmcnt(2)
	s_barrier
	v_lshlrev_b32_e32 v6, 15, v4
	v_and_b32_e32 v6, 0xffff0000, v6
	v_lshl_add_u32 v3, v3, 12, v6
	v_and_b32_e32 v4, 1, v4
	v_lshl_or_b32 v3, v4, 6, v3
	v_lshl_add_u32 v136, v5, 1, v3
	v_lshlrev_b32_e32 v3, 15, v0
	v_and_b32_e32 v3, 0xffff0000, v3
	v_lshl_add_u32 v1, v1, 12, v3
	v_and_b32_e32 v0, 1, v0
	v_readlane_b32 s5, v254, 19
	s_waitcnt vmcnt(6)
	v_lshl_or_b32 v0, v0, 6, v1
	s_mov_b32 s20, s4
	v_readlane_b32 s4, v253, 57
	v_lshl_add_u32 v138, v2, 1, v0
	v_mov_b32_e32 v0, 0
	v_readlane_b32 s5, v253, 58
	v_or_b32_e32 v214, s41, v216
	v_bitop3_b32 v144, s0, v14, v15 bitop3:0xf6
	v_mov_b32_e32 v137, v33
	v_mov_b32_e32 v139, v33
	s_mov_b32 s46, 0
	v_add_u32_e32 v145, 0, v16
	s_mov_b32 s0, s4
	s_mov_b64 s[4:5], s[12:13]
	v_mov_b32_e32 v1, v0
	v_mov_b32_e32 v2, v0
	v_mov_b32_e32 v3, v0
	v_mov_b32_e32 v4, v0
	v_mov_b32_e32 v5, v0
	v_mov_b32_e32 v6, v0
	v_mov_b32_e32 v7, v0
	v_mov_b32_e32 v16, v0
	v_mov_b32_e32 v17, v0
	v_mov_b32_e32 v18, v0
	v_mov_b32_e32 v19, v0
	v_mov_b32_e32 v20, v0
	v_mov_b32_e32 v21, v0
	v_mov_b32_e32 v22, v0
	v_mov_b32_e32 v23, v0
	v_mov_b32_e32 v34, v0
	v_mov_b32_e32 v35, v0
	v_mov_b32_e32 v36, v0
	v_mov_b32_e32 v37, v0
	v_mov_b32_e32 v38, v0
	v_mov_b32_e32 v39, v0
	v_mov_b32_e32 v40, v0
	v_mov_b32_e32 v41, v0
	v_mov_b32_e32 v50, v0
	v_mov_b32_e32 v51, v0
	v_mov_b32_e32 v52, v0
	v_mov_b32_e32 v53, v0
	v_mov_b32_e32 v58, v0
	v_mov_b32_e32 v59, v0
	v_mov_b32_e32 v60, v0
	v_mov_b32_e32 v61, v0
	v_mov_b32_e32 v8, v0
	v_mov_b32_e32 v9, v0
	v_mov_b32_e32 v10, v0
	v_mov_b32_e32 v11, v0
	v_mov_b32_e32 v12, v0
	v_mov_b32_e32 v13, v0
	v_mov_b32_e32 v14, v0
	v_mov_b32_e32 v15, v0
	v_mov_b32_e32 v24, v0
	v_mov_b32_e32 v25, v0
	v_mov_b32_e32 v26, v0
	v_mov_b32_e32 v27, v0
	v_mov_b32_e32 v28, v0
	v_mov_b32_e32 v29, v0
	v_mov_b32_e32 v30, v0
	v_mov_b32_e32 v31, v0
	v_mov_b32_e32 v42, v0
	v_mov_b32_e32 v43, v0
	v_mov_b32_e32 v44, v0
	v_mov_b32_e32 v45, v0
	v_mov_b32_e32 v46, v0
	v_mov_b32_e32 v47, v0
	v_mov_b32_e32 v48, v0
	v_mov_b32_e32 v49, v0
	v_mov_b32_e32 v66, v0
	v_mov_b32_e32 v67, v0
	v_mov_b32_e32 v68, v0
	v_mov_b32_e32 v69, v0
	v_mov_b32_e32 v74, v0
	v_mov_b32_e32 v75, v0
	v_mov_b32_e32 v76, v0
	v_mov_b32_e32 v77, v0
	v_mov_b32_e32 v94, v0
	v_mov_b32_e32 v95, v0
	v_mov_b32_e32 v96, v0
	v_mov_b32_e32 v97, v0
	v_mov_b32_e32 v102, v0
	v_mov_b32_e32 v103, v0
	v_mov_b32_e32 v104, v0
	v_mov_b32_e32 v105, v0
	v_mov_b32_e32 v118, v0
	v_mov_b32_e32 v119, v0
	v_mov_b32_e32 v120, v0
	v_mov_b32_e32 v121, v0
	v_mov_b32_e32 v114, v0
	v_mov_b32_e32 v115, v0
	v_mov_b32_e32 v116, v0
	v_mov_b32_e32 v117, v0
	v_mov_b32_e32 v98, v0
	v_mov_b32_e32 v99, v0
	v_mov_b32_e32 v100, v0
	v_mov_b32_e32 v101, v0
	v_mov_b32_e32 v90, v0
	v_mov_b32_e32 v91, v0
	v_mov_b32_e32 v92, v0
	v_mov_b32_e32 v93, v0
	v_mov_b32_e32 v78, v0
	v_mov_b32_e32 v79, v0
	v_mov_b32_e32 v80, v0
	v_mov_b32_e32 v81, v0
	v_mov_b32_e32 v70, v0
	v_mov_b32_e32 v71, v0
	v_mov_b32_e32 v72, v0
	v_mov_b32_e32 v73, v0
	v_mov_b32_e32 v122, v0
	v_mov_b32_e32 v123, v0
	v_mov_b32_e32 v124, v0
	v_mov_b32_e32 v125, v0
	v_mov_b32_e32 v126, v0
	v_mov_b32_e32 v127, v0
	v_mov_b32_e32 v128, v0
	v_mov_b32_e32 v129, v0
	v_mov_b32_e32 v110, v0
	v_mov_b32_e32 v111, v0
	v_mov_b32_e32 v112, v0
	v_mov_b32_e32 v113, v0
	v_mov_b32_e32 v106, v0
	v_mov_b32_e32 v107, v0
	v_mov_b32_e32 v108, v0
	v_mov_b32_e32 v109, v0
	v_mov_b32_e32 v86, v0
	v_mov_b32_e32 v87, v0
	v_mov_b32_e32 v88, v0
	v_mov_b32_e32 v89, v0
	v_mov_b32_e32 v82, v0
	v_mov_b32_e32 v83, v0
	v_mov_b32_e32 v84, v0
	v_mov_b32_e32 v85, v0
	v_mov_b32_e32 v62, v0
	v_mov_b32_e32 v63, v0
	v_mov_b32_e32 v64, v0
	v_mov_b32_e32 v65, v0
	v_mov_b32_e32 v54, v0
	v_mov_b32_e32 v55, v0
	v_mov_b32_e32 v56, v0
	v_mov_b32_e32 v57, v0
	s_barrier
	s_add_i32 s24, s46, 1
	s_cmp_eq_u32 s24, 0x7fffffff
	s_mov_b64 s[16:17], 0
	s_cbranch_scc0 .LBB0_1280
